# write-through (sc1) on the bf16 H stores of the three norm passes, on top of the combined page-contained variant
# speedup vs baseline: 1.0050x; 1.0050x over previous
; template <int MODE, bool XB> __device__ __forceinline__ void norm_pass(const void* __restrict__ X, const float* __restrict__ g, const float* __restrict__ shift, const float* __restrict__ scale, ...
;     ...
;         for (int r = 0; r < 16; ++r) {
;             f32x4 v[4]; float s = 0.f;
; #pragma unroll
;             for (int j = 0; j < 4; ++j) {
;                 if constexpr (XB) { const v2u w = *(const v2u*)((const bf16*)X + (size_t)(m0 + r) * D + 4 * lane + 256 * j);
;                     v[j] = (f32x4){__uint_as_float(w.x << 16), __uint_as_float(w.x & 0xffff0000u), __uint_as_float(w.y << 16), __uint_as_float(w.y & 0xffff0000u)}; }
;                 else v[j] = *(const f32x4*)((const float*)X + (size_t)(m0 + r) * D + 4 * lane + 256 * j);
;                 s += (v[j][0] * v[j][0] + v[j][1] * v[j][1]) + (v[j][2] * v[j][2] + v[j][3] * v[j][3]); }
;             const float rstd = 1.0f / sqrtf(wave_sum(s) * (1.f / D) + 1e-6f);
.LBB0_51:
	s_add_i32 s0, s54, s38
	global_load_dwordx4 v[32:35], v[126:127], off offset:-2048 nt
	global_load_dwordx4 v[36:39], v[126:127], off offset:-1024 nt
	global_load_dwordx4 v[40:43], v[126:127], off nt
	global_load_dwordx4 v[44:47], v[126:127], off offset:1024 nt
	s_add_i32 s4, s0, 17
	s_add_i32 s6, s0, 18
	s_add_i32 s0, s0, 19
	s_ashr_i32 s5, s4, 31
	s_ashr_i32 s7, s6, 31
	s_ashr_i32 s1, s0, 31
	s_lshl_b64 s[10:11], s[4:5], 12
	s_lshl_b64 s[12:13], s[6:7], 12
	s_lshl_b64 s[14:15], s[0:1], 12
	v_lshl_add_u64 v[48:49], v[96:97], 0, s[10:11]
	v_lshl_add_u64 v[50:51], v[96:97], 0, s[12:13]
	v_lshl_add_u64 v[56:57], v[96:97], 0, s[14:15]
	global_load_dwordx4 v[92:95], v[48:49], off nt
	global_load_dwordx4 v[84:87], v[48:49], off offset:1024 nt
	global_load_dwordx4 v[80:83], v[48:49], off offset:3072 nt
	global_load_dwordx4 v[88:91], v[48:49], off offset:2048 nt
	global_load_dwordx4 v[76:79], v[50:51], off nt
	global_load_dwordx4 v[68:71], v[50:51], off offset:1024 nt
	global_load_dwordx4 v[64:67], v[50:51], off offset:3072 nt
	global_load_dwordx4 v[72:75], v[50:51], off offset:2048 nt
	global_load_dwordx4 v[60:63], v[56:57], off nt
	global_load_dwordx4 v[52:55], v[56:57], off offset:1024 nt
	s_nop 0
	global_load_dwordx4 v[48:51], v[56:57], off offset:3072 nt
	s_nop 0
	global_load_dwordx4 v[56:59], v[56:57], off offset:2048 nt
	s_lshl_b64 s[0:1], s[0:1], 11
	s_lshl_b64 s[4:5], s[4:5], 11
	s_lshl_b64 s[6:7], s[6:7], 11
	v_lshl_add_u64 v[128:129], v[98:99], 0, s[0:1]
	v_lshl_add_u64 v[132:133], v[98:99], 0, s[4:5]
	v_lshl_add_u64 v[130:131], v[98:99], 0, s[6:7]
	s_add_i32 s38, s38, 4
	v_lshl_add_u64 v[126:127], v[126:127], 0, s[74:75]
	s_cmp_lg_u32 s38, 0
	s_waitcnt vmcnt(15)
	v_pk_mul_f32 v[144:145], v[34:35], v[34:35]
	v_pk_mul_f32 v[146:147], v[32:33], v[32:33]
	s_waitcnt vmcnt(14)
	v_pk_mul_f32 v[148:149], v[38:39], v[38:39]
	v_pk_mul_f32 v[150:151], v[36:37], v[36:37]
	v_pk_mov_b32 v[156:157], v[146:147], v[144:145] op_sel:[1,0]
	v_mov_b32_e32 v147, v145
	v_pk_mov_b32 v[144:145], v[150:151], v[148:149] op_sel:[1,0]
	v_mov_b32_e32 v151, v149
	s_waitcnt vmcnt(12)
	v_mul_f32_e32 v155, v45, v45
	v_mul_f32_e32 v152, v41, v41
	v_mul_f32_e32 v154, v43, v43
	v_pk_add_f32 v[146:147], v[156:157], v[146:147]
	v_pk_add_f32 v[144:145], v[144:145], v[150:151]
	v_mul_f32_e32 v143, v44, v44
	v_mul_f32_e32 v158, v46, v46
	v_mul_f32_e32 v159, v47, v47
	v_pk_fma_f32 v[148:149], v[40:41], v[40:41], v[152:153] op_sel_hi:[1,1,0]
	v_pk_fma_f32 v[152:153], v[42:43], v[42:43], v[154:155] op_sel_hi:[1,1,0]
	v_pk_add_f32 v[146:147], v[146:147], v[146:147] op_sel:[0,1] op_sel_hi:[1,0]
	v_pk_add_f32 v[144:145], v[144:145], v[144:145] op_sel:[0,1] op_sel_hi:[1,0]
	v_mov_b32_e32 v149, v158
	v_mov_b32_e32 v153, v159
	v_mov_b32_e32 v147, v143
	v_mov_b32_e32 v145, v155
	v_pk_add_f32 v[148:149], v[148:149], v[152:153]
	v_pk_add_f32 v[144:145], v[146:147], v[144:145]
	s_waitcnt vmcnt(11)
	v_pk_mul_f32 v[146:147], v[94:95], v[94:95]
	v_pk_mul_f32 v[150:151], v[92:93], v[92:93]
	s_waitcnt vmcnt(10)
	v_pk_mul_f32 v[152:153], v[86:87], v[86:87]
	v_pk_mul_f32 v[154:155], v[84:85], v[84:85]
	s_waitcnt vmcnt(9)
	v_mul_f32_e32 v183, v81, v81
	s_waitcnt vmcnt(8)
	v_mul_f32_e32 v156, v89, v89
	v_mul_f32_e32 v158, v91, v91
	s_waitcnt vmcnt(7)
	v_pk_mul_f32 v[160:161], v[78:79], v[78:79]
	v_pk_mul_f32 v[162:163], v[76:77], v[76:77]
	s_waitcnt vmcnt(6)
	v_pk_mul_f32 v[164:165], v[70:71], v[70:71]
	v_pk_mul_f32 v[166:167], v[68:69], v[68:69]
	s_waitcnt vmcnt(4)
	v_mul_f32_e32 v168, v73, v73
	v_mul_f32_e32 v170, v75, v75
	s_waitcnt vmcnt(3)
	v_pk_mul_f32 v[172:173], v[62:63], v[62:63]
	v_pk_mul_f32 v[174:175], v[60:61], v[60:61]
	s_waitcnt vmcnt(2)
	v_pk_mul_f32 v[176:177], v[54:55], v[54:55]
	v_pk_mul_f32 v[178:179], v[52:53], v[52:53]
	s_waitcnt vmcnt(0)
	v_mul_f32_e32 v180, v57, v57
	v_mul_f32_e32 v182, v59, v59
	v_pk_add_f32 v[144:145], v[144:145], v[148:149]
	v_pk_mov_b32 v[148:149], v[150:151], v[146:147] op_sel:[1,0]
	v_mov_b32_e32 v151, v147
	v_pk_mov_b32 v[146:147], v[154:155], v[152:153] op_sel:[1,0]
	v_mov_b32_e32 v155, v153
	v_pk_fma_f32 v[152:153], v[88:89], v[88:89], v[156:157] op_sel_hi:[1,1,0]
	v_pk_fma_f32 v[156:157], v[90:91], v[90:91], v[158:159] op_sel_hi:[1,1,0]
	v_pk_mov_b32 v[158:159], v[162:163], v[160:161] op_sel:[1,0]
	v_mov_b32_e32 v163, v161
	v_pk_mov_b32 v[160:161], v[166:167], v[164:165] op_sel:[1,0]
	v_mov_b32_e32 v167, v165
	v_pk_fma_f32 v[164:165], v[72:73], v[72:73], v[168:169] op_sel_hi:[1,1,0]
	v_pk_fma_f32 v[168:169], v[74:75], v[74:75], v[170:171] op_sel_hi:[1,1,0]
	v_pk_mov_b32 v[170:171], v[174:175], v[172:173] op_sel:[1,0]
	v_mov_b32_e32 v175, v173
	v_pk_mov_b32 v[172:173], v[178:179], v[176:177] op_sel:[1,0]
	v_mov_b32_e32 v179, v177
	v_pk_fma_f32 v[176:177], v[56:57], v[56:57], v[180:181] op_sel_hi:[1,1,0]
	v_pk_fma_f32 v[180:181], v[58:59], v[58:59], v[182:183] op_sel_hi:[1,1,0]
	v_add_f32_e32 v182, v144, v145
	v_pk_add_f32 v[144:145], v[148:149], v[150:151]
	v_pk_add_f32 v[146:147], v[146:147], v[154:155]
	v_pk_add_f32 v[148:149], v[158:159], v[162:163]
	v_pk_add_f32 v[150:151], v[160:161], v[166:167]
	ds_bpermute_b32 v162, v134, v182
	v_mul_f32_e32 v143, v80, v80
	v_mul_f32_e32 v184, v82, v82
	v_mul_f32_e32 v185, v83, v83
	v_mul_f32_e32 v186, v64, v64
	v_mul_f32_e32 v187, v65, v65
	v_mul_f32_e32 v190, v66, v66
	v_mul_f32_e32 v191, v67, v67
	v_pk_add_f32 v[154:155], v[170:171], v[174:175]
	v_pk_add_f32 v[158:159], v[172:173], v[178:179]
	v_pk_add_f32 v[144:145], v[144:145], v[144:145] op_sel:[0,1] op_sel_hi:[1,0]
	v_pk_add_f32 v[146:147], v[146:147], v[146:147] op_sel:[0,1] op_sel_hi:[1,0]
	v_pk_add_f32 v[148:149], v[148:149], v[148:149] op_sel:[0,1] op_sel_hi:[1,0]
	v_pk_add_f32 v[150:151], v[150:151], v[150:151] op_sel:[0,1] op_sel_hi:[1,0]
	v_mul_f32_e32 v192, v48, v48
	v_mul_f32_e32 v193, v49, v49
	v_mul_f32_e32 v194, v50, v50
	v_mul_f32_e32 v195, v51, v51
	v_mov_b32_e32 v153, v184
	v_mov_b32_e32 v157, v185
	v_mov_b32_e32 v165, v190
	v_mov_b32_e32 v169, v191
	v_pk_add_f32 v[154:155], v[154:155], v[154:155] op_sel:[0,1] op_sel_hi:[1,0]
	v_pk_add_f32 v[158:159], v[158:159], v[158:159] op_sel:[0,1] op_sel_hi:[1,0]
	v_mov_b32_e32 v145, v143
	v_mov_b32_e32 v147, v183
	v_mov_b32_e32 v149, v186
	v_mov_b32_e32 v151, v187
	v_mov_b32_e32 v177, v194
	v_mov_b32_e32 v181, v195
	v_pk_add_f32 v[152:153], v[152:153], v[156:157]
	v_pk_add_f32 v[156:157], v[164:165], v[168:169]
	v_mov_b32_e32 v155, v192
	v_mov_b32_e32 v159, v193
	v_pk_add_f32 v[144:145], v[144:145], v[146:147]
	v_pk_add_f32 v[146:147], v[148:149], v[150:151]
	v_pk_add_f32 v[160:161], v[176:177], v[180:181]
	v_pk_add_f32 v[148:149], v[154:155], v[158:159]
	v_pk_add_f32 v[144:145], v[144:145], v[152:153]
	v_pk_add_f32 v[146:147], v[146:147], v[156:157]
	v_pk_add_f32 v[148:149], v[148:149], v[160:161]
	v_add_f32_e32 v143, v144, v145
	v_add_f32_e32 v144, v146, v147
	s_waitcnt lgkmcnt(0)
; template <int MODE, bool XB> __device__ __forceinline__ void norm_pass(const void* __restrict__ X, const float* __restrict__ g, const float* __restrict__ shift, const float* __restrict__ scale, ...
;     ...
;             f32x4 v[4]; float s = 0.f;
; #pragma unroll
;             for (int j = 0; j < 4; ++j) {
;                 if constexpr (XB) { const v2u w = *(const v2u*)((const bf16*)X + (size_t)(m0 + r) * D + 4 * lane + 256 * j);
;                     v[j] = (f32x4){__uint_as_float(w.x << 16), __uint_as_float(w.x & 0xffff0000u), __uint_as_float(w.y << 16), __uint_as_float(w.y & 0xffff0000u)}; }
;                 else v[j] = *(const f32x4*)((const float*)X + (size_t)(m0 + r) * D + 4 * lane + 256 * j);
;                 s += (v[j][0] * v[j][0] + v[j][1] * v[j][1]) + (v[j][2] * v[j][2] + v[j][3] * v[j][3]); }
;             const float rstd = 1.0f / sqrtf(wave_sum(s) * (1.f / D) + 1e-6f);
	v_add_f32_e32 v146, v182, v162
	v_add_f32_e32 v145, v148, v149
	ds_bpermute_b32 v147, v134, v143
	ds_bpermute_b32 v150, v135, v146
	ds_bpermute_b32 v148, v134, v144
	ds_bpermute_b32 v149, v134, v145
	s_waitcnt lgkmcnt(3)
	v_add_f32_e32 v143, v143, v147
	s_waitcnt lgkmcnt(2)
	v_add_f32_e32 v146, v146, v150
	s_waitcnt lgkmcnt(1)
	v_add_f32_e32 v144, v144, v148
	s_waitcnt lgkmcnt(0)
	v_add_f32_e32 v145, v145, v149
	ds_bpermute_b32 v147, v135, v143
	ds_bpermute_b32 v150, v136, v146
	ds_bpermute_b32 v148, v135, v144
	ds_bpermute_b32 v149, v135, v145
	s_waitcnt lgkmcnt(3)
	v_add_f32_e32 v143, v143, v147
	s_waitcnt lgkmcnt(2)
	v_add_f32_e32 v146, v146, v150
	s_waitcnt lgkmcnt(1)
	v_add_f32_e32 v144, v144, v148
	s_waitcnt lgkmcnt(0)
	v_add_f32_e32 v145, v145, v149
	ds_bpermute_b32 v147, v136, v143
	ds_bpermute_b32 v150, v137, v146
	ds_bpermute_b32 v148, v136, v144
	ds_bpermute_b32 v149, v136, v145
	s_waitcnt lgkmcnt(3)
	v_add_f32_e32 v143, v143, v147
	s_waitcnt lgkmcnt(2)
	v_add_f32_e32 v146, v146, v150
	s_waitcnt lgkmcnt(1)
	v_add_f32_e32 v144, v144, v148
	s_waitcnt lgkmcnt(0)
	v_add_f32_e32 v145, v145, v149
	ds_bpermute_b32 v147, v137, v143
	ds_bpermute_b32 v150, v138, v146
	ds_bpermute_b32 v148, v137, v144
	ds_bpermute_b32 v149, v137, v145
	s_waitcnt lgkmcnt(3)
	v_add_f32_e32 v143, v143, v147
	s_waitcnt lgkmcnt(2)
	v_add_f32_e32 v146, v146, v150
	s_waitcnt lgkmcnt(1)
	v_add_f32_e32 v144, v144, v148
	s_waitcnt lgkmcnt(0)
	v_add_f32_e32 v145, v145, v149
	ds_bpermute_b32 v147, v138, v143
	ds_bpermute_b32 v150, v139, v146
	ds_bpermute_b32 v148, v138, v144
	ds_bpermute_b32 v149, v138, v145
	s_waitcnt lgkmcnt(3)
	v_add_f32_e32 v143, v143, v147
	s_waitcnt lgkmcnt(2)
	v_add_f32_e32 v146, v146, v150
	s_waitcnt lgkmcnt(1)
	v_add_f32_e32 v144, v144, v148
	s_waitcnt lgkmcnt(0)
	v_add_f32_e32 v145, v145, v149
	ds_bpermute_b32 v147, v139, v143
	v_fmamk_f32 v146, v146, 0x3a800000, v141
	ds_bpermute_b32 v148, v139, v144
	ds_bpermute_b32 v149, v139, v145
	v_mul_f32_e32 v150, 0x4f800000, v146
	v_cmp_gt_f32_e32 vcc, s33, v146
	s_waitcnt lgkmcnt(2)
	v_add_f32_e32 v143, v143, v147
	s_waitcnt lgkmcnt(1)
	v_add_f32_e32 v144, v144, v148
	v_cndmask_b32_e32 v146, v146, v150, vcc
	v_sqrt_f32_e32 v150, v146
	s_waitcnt lgkmcnt(0)
	v_add_f32_e32 v145, v145, v149
	v_fmamk_f32 v143, v143, 0x3a800000, v141
	v_fmamk_f32 v144, v144, 0x3a800000, v141
	v_fmamk_f32 v145, v145, 0x3a800000, v141
	v_mul_f32_e32 v147, 0x4f800000, v143
	v_cmp_gt_f32_e64 s[0:1], s33, v143
	v_add_u32_e32 v151, -1, v150
	v_mul_f32_e32 v148, 0x4f800000, v144
	v_cmp_gt_f32_e64 s[4:5], s33, v144
	v_mul_f32_e32 v149, 0x4f800000, v145
	v_cmp_gt_f32_e64 s[6:7], s33, v145
	v_add_u32_e32 v152, 1, v150
	v_cndmask_b32_e64 v143, v143, v147, s[0:1]
	v_fma_f32 v147, -v151, v150, v146
	v_cndmask_b32_e64 v144, v144, v148, s[4:5]
	v_cndmask_b32_e64 v145, v145, v149, s[6:7]
	v_fma_f32 v148, -v152, v150, v146
	v_cmp_ge_f32_e64 s[10:11], 0, v147
	v_sqrt_f32_e32 v149, v143
	v_sqrt_f32_e32 v154, v145
	v_cndmask_b32_e64 v147, v150, v151, s[10:11]
	v_cmp_lt_f32_e64 s[10:11], 0, v148
	v_sqrt_f32_e32 v153, v144
	v_add_u32_e32 v155, -1, v154
	v_cndmask_b32_e64 v147, v147, v152, s[10:11]
	v_mul_f32_e32 v148, 0x37800000, v147
	v_cndmask_b32_e32 v147, v147, v148, vcc
	v_cmp_class_f32_e32 vcc, v146, v142
	v_add_u32_e32 v148, -1, v149
	v_add_u32_e32 v150, 1, v149
	v_cndmask_b32_e32 v146, v147, v146, vcc
	v_add_u32_e32 v151, -1, v153
	v_add_u32_e32 v156, 1, v154
	v_fma_f32 v147, -v148, v149, v143
	v_fma_f32 v160, -v155, v154, v145
	v_div_scale_f32 v162, s[10:11], v146, v146, 1.0
	v_add_u32_e32 v152, 1, v153
	v_fma_f32 v157, -v150, v149, v143
	v_fma_f32 v158, -v151, v153, v144
	v_fma_f32 v161, -v156, v154, v145
	v_cmp_ge_f32_e64 s[10:11], 0, v147
	v_cmp_ge_f32_e64 s[14:15], 0, v160
	v_fma_f32 v159, -v152, v153, v144
	v_cndmask_b32_e64 v147, v149, v148, s[10:11]
	v_cmp_lt_f32_e64 s[10:11], 0, v157
	v_cmp_ge_f32_e64 s[12:13], 0, v158
	v_cndmask_b32_e64 v149, v154, v155, s[14:15]
	v_cmp_lt_f32_e64 s[14:15], 0, v161
	v_cndmask_b32_e64 v148, v153, v151, s[12:13]
	v_cmp_lt_f32_e64 s[12:13], 0, v159
	v_rcp_f32_e32 v151, v162
	v_cndmask_b32_e64 v147, v147, v150, s[10:11]
	v_cndmask_b32_e64 v149, v149, v156, s[14:15]
	v_cndmask_b32_e64 v148, v148, v152, s[12:13]
	v_mul_f32_e32 v150, 0x37800000, v147
	v_mul_f32_e32 v153, 0x37800000, v149
	v_mul_f32_e32 v152, 0x37800000, v148
	v_cndmask_b32_e64 v147, v147, v150, s[0:1]
	v_cndmask_b32_e64 v149, v149, v153, s[6:7]
	v_cmp_class_f32_e64 s[6:7], v143, v142
	v_cndmask_b32_e64 v148, v148, v152, s[4:5]
	v_cmp_class_f32_e64 s[0:1], v144, v142
	v_cmp_class_f32_e64 s[4:5], v145, v142
	v_cndmask_b32_e64 v143, v147, v143, s[6:7]
	v_cndmask_b32_e64 v147, v148, v144, s[0:1]
	v_cndmask_b32_e64 v145, v149, v145, s[4:5]
	v_fma_f32 v144, -v162, v151, 1.0
	v_div_scale_f32 v148, s[0:1], v143, v143, 1.0
	v_div_scale_f32 v163, vcc, 1.0, v146, 1.0
	v_div_scale_f32 v153, s[0:1], v145, v145, 1.0
	v_fmac_f32_e32 v151, v144, v151
	v_rcp_f32_e32 v155, v148
	v_div_scale_f32 v150, s[0:1], v147, v147, 1.0
	v_rcp_f32_e32 v157, v153
	v_mul_f32_e32 v144, v163, v151
	v_rcp_f32_e32 v156, v150
	v_fma_f32 v158, -v162, v144, v163
	v_fmac_f32_e32 v144, v158, v151
	v_fma_f32 v158, -v162, v144, v163
	v_fma_f32 v159, -v148, v155, 1.0
	v_div_scale_f32 v149, s[4:5], 1.0, v143, 1.0
	v_fma_f32 v161, -v153, v157, 1.0
	v_div_fmas_f32 v144, v158, v151, v144
	v_fmac_f32_e32 v155, v159, v155
	v_div_scale_f32 v154, s[0:1], 1.0, v145, 1.0
	v_fma_f32 v160, -v150, v156, 1.0
	v_fmac_f32_e32 v157, v161, v157
	v_div_fixup_f32 v144, v144, v146, 1.0
	v_mul_f32_e32 v146, v149, v155
	v_div_scale_f32 v152, s[6:7], 1.0, v147, 1.0
	v_fmac_f32_e32 v156, v160, v156
; __device__ __forceinline__ unsigned pk2(float lo, float hi) { return f2bf(lo) | (f2bf(hi) << 16); }
; template <int MODE, bool XB> __device__ __forceinline__ void norm_pass(const void* __restrict__ X, const float* __restrict__ g, const float* __restrict__ shift, const float* __restrict__ scale, ...
;     ...
;             const float rstd = 1.0f / sqrtf(wave_sum(s) * (1.f / D) + 1e-6f);
; #pragma unroll
;             for (int j = 0; j < 4; ++j) {
;                 if (MODE == 0) { const f32x4 o = v[j] * rstd * gm[j] + sh[j]; v2u w; w.x = pk2(o[0], o[1]); w.y = pk2(o[2], o[3]); *(v2u*)(Hb + (size_t)(m0 + r) * D + 4 * lane + 256 * j) = w; }
	v_mul_f32_e32 v158, v154, v157
	v_pk_mul_f32 v[32:33], v[32:33], v[144:145] op_sel_hi:[1,0]
	v_pk_mul_f32 v[34:35], v[34:35], v[144:145] op_sel_hi:[1,0]
	v_pk_mul_f32 v[36:37], v[36:37], v[144:145] op_sel_hi:[1,0]
	v_pk_mul_f32 v[38:39], v[38:39], v[144:145] op_sel_hi:[1,0]
	v_pk_mul_f32 v[40:41], v[40:41], v[144:145] op_sel_hi:[1,0]
	v_pk_mul_f32 v[42:43], v[42:43], v[144:145] op_sel_hi:[1,0]
	v_pk_mul_f32 v[44:45], v[44:45], v[144:145] op_sel_hi:[1,0]
	v_pk_mul_f32 v[46:47], v[46:47], v[144:145] op_sel_hi:[1,0]
	v_fma_f32 v144, -v148, v146, v149
	v_mul_f32_e32 v151, v152, v156
	v_fma_f32 v160, -v153, v158, v154
	v_pk_fma_f32 v[34:35], v[110:111], v[34:35], v[18:19]
	v_pk_fma_f32 v[32:33], v[112:113], v[32:33], v[16:17]
	v_pk_fma_f32 v[38:39], v[114:115], v[38:39], v[22:23]
	v_pk_fma_f32 v[36:37], v[116:117], v[36:37], v[20:21]
	v_pk_fma_f32 v[42:43], v[118:119], v[42:43], v[26:27]
	v_fmac_f32_e32 v146, v144, v155
	v_fma_f32 v159, -v150, v151, v152
	v_pk_fma_f32 v[40:41], v[120:121], v[40:41], v[24:25]
	v_pk_fma_f32 v[46:47], v[122:123], v[46:47], v[30:31]
	v_pk_fma_f32 v[44:45], v[124:125], v[44:45], v[28:29]
	v_fmac_f32_e32 v158, v160, v157
	v_bfe_u32 v144, v32, 16, 1
	v_bfe_u32 v160, v34, 16, 1
	v_bfe_u32 v162, v36, 16, 1
	v_bfe_u32 v164, v38, 16, 1
	v_bfe_u32 v168, v42, 16, 1
	v_fma_f32 v148, -v148, v146, v149
	s_mov_b64 vcc, s[4:5]
	v_fmac_f32_e32 v151, v159, v156
	v_bfe_u32 v159, v33, 16, 1
	v_bfe_u32 v161, v35, 16, 1
	v_bfe_u32 v163, v37, 16, 1
	v_bfe_u32 v165, v39, 16, 1
	v_bfe_u32 v166, v40, 16, 1
	v_bfe_u32 v169, v43, 16, 1
	v_bfe_u32 v170, v44, 16, 1
	v_bfe_u32 v172, v46, 16, 1
	v_add3_u32 v32, v32, v144, s36
	v_add3_u32 v34, v34, v160, s36
	v_add3_u32 v36, v36, v162, s36
	v_add3_u32 v38, v38, v164, s36
	v_add3_u32 v42, v42, v168, s36
	v_div_fmas_f32 v144, v148, v155, v146
	v_bfe_u32 v167, v41, 16, 1
	v_bfe_u32 v171, v45, 16, 1
	v_bfe_u32 v173, v47, 16, 1
	v_fma_f32 v149, -v150, v151, v152
	v_add3_u32 v33, v33, v159, s36
	v_add3_u32 v35, v35, v161, s36
	v_add3_u32 v37, v37, v163, s36
	v_add3_u32 v39, v39, v165, s36
	v_add3_u32 v40, v40, v166, s36
	v_add3_u32 v43, v43, v169, s36
	v_add3_u32 v44, v44, v170, s36
	v_add3_u32 v46, v46, v172, s36
	v_lshrrev_b32_e32 v146, 16, v32
	v_lshrrev_b32_e32 v148, 16, v34
	v_lshrrev_b32_e32 v36, 16, v36
	v_lshrrev_b32_e32 v38, 16, v38
	v_lshrrev_b32_e32 v42, 16, v42
	v_div_fixup_f32 v32, v144, v143, 1.0
	s_mov_b64 vcc, s[6:7]
	v_fma_f32 v150, -v153, v158, v154
	v_add3_u32 v41, v41, v167, s36
	v_add3_u32 v45, v45, v171, s36
	v_add3_u32 v47, v47, v173, s36
	v_lshrrev_b32_e32 v40, 16, v40
	v_lshrrev_b32_e32 v44, 16, v44
	v_lshrrev_b32_e32 v46, 16, v46
	v_div_fmas_f32 v143, v149, v156, v151
	v_and_or_b32 v34, v33, s37, v146
	v_and_or_b32 v35, v35, s37, v148
	v_and_or_b32 v36, v37, s37, v36
	v_and_or_b32 v37, v39, s37, v38
	v_and_or_b32 v39, v43, s37, v42
	v_pk_mul_f32 v[42:43], v[92:93], v[32:33] op_sel_hi:[1,0]
	s_mov_b64 vcc, s[0:1]
	v_and_or_b32 v38, v41, s37, v40
	v_and_or_b32 v40, v45, s37, v44
	v_and_or_b32 v41, v47, s37, v46
	v_pk_mul_f32 v[44:45], v[94:95], v[32:33] op_sel_hi:[1,0]
	v_pk_mul_f32 v[46:47], v[84:85], v[32:33] op_sel_hi:[1,0]
	v_pk_mul_f32 v[84:85], v[86:87], v[32:33] op_sel_hi:[1,0]
	v_pk_mul_f32 v[86:87], v[88:89], v[32:33] op_sel_hi:[1,0]
	v_pk_mul_f32 v[88:89], v[90:91], v[32:33] op_sel_hi:[1,0]
	v_pk_mul_f32 v[80:81], v[80:81], v[32:33] op_sel_hi:[1,0]
	v_pk_mul_f32 v[32:33], v[82:83], v[32:33] op_sel_hi:[1,0]
	v_div_fixup_f32 v82, v143, v147, 1.0
	v_div_fmas_f32 v83, v150, v157, v158
	global_store_dwordx2 v[108:109], v[34:35], off offset:-1024 sc1
	global_store_dwordx2 v[108:109], v[36:37], off offset:-512 sc1
	global_store_dwordx2 v[108:109], v[38:39], off sc1
	global_store_dwordx2 v[108:109], v[40:41], off offset:512 sc1
	v_pk_fma_f32 v[36:37], v[112:113], v[42:43], v[16:17]
	v_pk_fma_f32 v[34:35], v[110:111], v[44:45], v[18:19]
	v_pk_fma_f32 v[38:39], v[114:115], v[84:85], v[22:23]
	v_pk_fma_f32 v[40:41], v[116:117], v[46:47], v[20:21]
	v_pk_fma_f32 v[42:43], v[118:119], v[88:89], v[26:27]
	v_pk_fma_f32 v[44:45], v[120:121], v[86:87], v[24:25]
	v_pk_fma_f32 v[32:33], v[122:123], v[32:33], v[30:31]
	v_pk_fma_f32 v[46:47], v[124:125], v[80:81], v[28:29]
	v_pk_mul_f32 v[76:77], v[76:77], v[82:83] op_sel_hi:[1,0]
	v_pk_mul_f32 v[78:79], v[78:79], v[82:83] op_sel_hi:[1,0]
	v_pk_mul_f32 v[68:69], v[68:69], v[82:83] op_sel_hi:[1,0]
	v_pk_mul_f32 v[70:71], v[70:71], v[82:83] op_sel_hi:[1,0]
	v_pk_mul_f32 v[72:73], v[72:73], v[82:83] op_sel_hi:[1,0]
	v_pk_mul_f32 v[74:75], v[74:75], v[82:83] op_sel_hi:[1,0]
	v_div_fixup_f32 v80, v83, v145, 1.0
	v_bfe_u32 v81, v36, 16, 1
	v_pk_mul_f32 v[64:65], v[64:65], v[82:83] op_sel_hi:[1,0]
	v_pk_mul_f32 v[66:67], v[66:67], v[82:83] op_sel_hi:[1,0]
	v_bfe_u32 v82, v37, 16, 1
	v_bfe_u32 v83, v34, 16, 1
	v_bfe_u32 v84, v35, 16, 1
	v_bfe_u32 v85, v40, 16, 1
	v_bfe_u32 v86, v41, 16, 1
	v_bfe_u32 v87, v38, 16, 1
	v_bfe_u32 v88, v39, 16, 1
	v_bfe_u32 v89, v44, 16, 1
	v_bfe_u32 v90, v45, 16, 1
	v_bfe_u32 v91, v42, 16, 1
	v_bfe_u32 v92, v43, 16, 1
	v_bfe_u32 v93, v46, 16, 1
	v_bfe_u32 v94, v47, 16, 1
	v_bfe_u32 v95, v32, 16, 1
	v_bfe_u32 v143, v33, 16, 1
	v_pk_fma_f32 v[78:79], v[110:111], v[78:79], v[18:19]
	v_pk_fma_f32 v[76:77], v[112:113], v[76:77], v[16:17]
	v_pk_fma_f32 v[70:71], v[114:115], v[70:71], v[22:23]
	v_pk_fma_f32 v[68:69], v[116:117], v[68:69], v[20:21]
	v_pk_fma_f32 v[74:75], v[118:119], v[74:75], v[26:27]
	v_pk_fma_f32 v[72:73], v[120:121], v[72:73], v[24:25]
	v_pk_mul_f32 v[60:61], v[60:61], v[80:81] op_sel_hi:[1,0]
	v_pk_mul_f32 v[62:63], v[62:63], v[80:81] op_sel_hi:[1,0]
	v_pk_fma_f32 v[66:67], v[122:123], v[66:67], v[30:31]
; __device__ __forceinline__ unsigned pk2(float lo, float hi) { return f2bf(lo) | (f2bf(hi) << 16); }
; template <int MODE, bool XB> __device__ __forceinline__ void norm_pass(const void* __restrict__ X, const float* __restrict__ g, const float* __restrict__ shift, const float* __restrict__ scale, ...
;     ...
;     for (int m0 = gw * 16; m0 < M; m0 += NGW * 16) {
;         const int b = m0 / SEQ;
;         f32x4 gm[4], sh[4];
; #pragma unroll
;         for (int j = 0; j < 4; ++j) { const int col = 4 * lane + 256 * j; gm[j] = *(const f32x4*)(g + col);
;             if (MODE == 0) { gm[j] = gm[j] * (*(const f32x4*)(scale + (size_t)b * NMOD9 + col) + 1.0f); sh[j] = *(const f32x4*)(shift + (size_t)b * NMOD9 + col); } }
; #pragma unroll 4
;         for (int r = 0; r < 16; ++r) {
;     ...
;             for (int j = 0; j < 4; ++j) {
;                 if (MODE == 0) { const f32x4 o = v[j] * rstd * gm[j] + sh[j]; v2u w; w.x = pk2(o[0], o[1]); w.y = pk2(o[2], o[3]); *(v2u*)(Hb + (size_t)(m0 + r) * D + 4 * lane + 256 * j) = w; }
	v_pk_fma_f32 v[64:65], v[124:125], v[64:65], v[28:29]
	v_pk_mul_f32 v[52:53], v[52:53], v[80:81] op_sel_hi:[1,0]
	v_pk_mul_f32 v[54:55], v[54:55], v[80:81] op_sel_hi:[1,0]
	v_pk_mul_f32 v[56:57], v[56:57], v[80:81] op_sel_hi:[1,0]
	v_pk_mul_f32 v[58:59], v[58:59], v[80:81] op_sel_hi:[1,0]
	v_pk_mul_f32 v[48:49], v[48:49], v[80:81] op_sel_hi:[1,0]
	v_pk_mul_f32 v[50:51], v[50:51], v[80:81] op_sel_hi:[1,0]
	v_add3_u32 v80, v36, v81, s36
	v_add3_u32 v81, v37, v82, s36
	v_add3_u32 v82, v34, v83, s36
	v_add3_u32 v83, v35, v84, s36
	v_add3_u32 v84, v40, v85, s36
	v_add3_u32 v85, v41, v86, s36
	v_add3_u32 v86, v38, v87, s36
	v_add3_u32 v87, v39, v88, s36
	v_add3_u32 v88, v44, v89, s36
	v_add3_u32 v89, v45, v90, s36
	v_add3_u32 v90, v42, v91, s36
	v_add3_u32 v91, v43, v92, s36
	v_add3_u32 v92, v46, v93, s36
	v_add3_u32 v93, v47, v94, s36
	v_add3_u32 v94, v32, v95, s36
	v_add3_u32 v95, v33, v143, s36
	v_bfe_u32 v143, v76, 16, 1
	v_bfe_u32 v145, v78, 16, 1
	v_bfe_u32 v147, v68, 16, 1
	v_bfe_u32 v149, v70, 16, 1
	v_bfe_u32 v151, v72, 16, 1
	v_bfe_u32 v153, v74, 16, 1
	v_pk_fma_f32 v[32:33], v[110:111], v[62:63], v[18:19]
	v_pk_fma_f32 v[34:35], v[112:113], v[60:61], v[16:17]
	v_bfe_u32 v144, v77, 16, 1
	v_bfe_u32 v146, v79, 16, 1
	v_bfe_u32 v148, v69, 16, 1
	v_bfe_u32 v150, v71, 16, 1
	v_bfe_u32 v152, v73, 16, 1
	v_bfe_u32 v154, v75, 16, 1
	v_bfe_u32 v155, v64, 16, 1
	v_bfe_u32 v157, v66, 16, 1
	v_pk_fma_f32 v[36:37], v[114:115], v[54:55], v[22:23]
	v_pk_fma_f32 v[38:39], v[116:117], v[52:53], v[20:21]
	v_pk_fma_f32 v[40:41], v[118:119], v[58:59], v[26:27]
	v_pk_fma_f32 v[42:43], v[120:121], v[56:57], v[24:25]
	v_pk_fma_f32 v[44:45], v[122:123], v[50:51], v[30:31]
	v_pk_fma_f32 v[46:47], v[124:125], v[48:49], v[28:29]
	v_lshrrev_b32_e32 v48, 16, v80
	v_lshrrev_b32_e32 v49, 16, v82
	v_add3_u32 v56, v76, v143, s36
	v_add3_u32 v58, v78, v145, s36
	v_add3_u32 v60, v68, v147, s36
	v_add3_u32 v62, v70, v149, s36
	v_add3_u32 v68, v72, v151, s36
	v_add3_u32 v70, v74, v153, s36
	v_bfe_u32 v72, v34, 16, 1
	v_bfe_u32 v74, v32, 16, 1
	v_bfe_u32 v156, v65, 16, 1
	v_bfe_u32 v158, v67, 16, 1
	v_lshrrev_b32_e32 v50, 16, v84
	v_lshrrev_b32_e32 v51, 16, v86
	v_lshrrev_b32_e32 v52, 16, v88
	v_lshrrev_b32_e32 v53, 16, v90
	v_lshrrev_b32_e32 v54, 16, v92
	v_lshrrev_b32_e32 v55, 16, v94
	v_add3_u32 v57, v77, v144, s36
	v_add3_u32 v59, v79, v146, s36
	v_add3_u32 v61, v69, v148, s36
	v_add3_u32 v63, v71, v150, s36
	v_add3_u32 v69, v73, v152, s36
	v_add3_u32 v71, v75, v154, s36
	v_add3_u32 v64, v64, v155, s36
	v_add3_u32 v66, v66, v157, s36
	v_bfe_u32 v73, v35, 16, 1
	v_bfe_u32 v75, v33, 16, 1
	v_bfe_u32 v76, v38, 16, 1
	v_bfe_u32 v78, v36, 16, 1
	v_bfe_u32 v80, v42, 16, 1
	v_bfe_u32 v84, v40, 16, 1
	v_bfe_u32 v88, v46, 16, 1
	v_bfe_u32 v92, v44, 16, 1
	v_and_or_b32 v48, v81, s37, v48
	v_and_or_b32 v49, v83, s37, v49
	v_lshrrev_b32_e32 v56, 16, v56
	v_lshrrev_b32_e32 v58, 16, v58
	v_add3_u32 v72, v34, v72, s36
	v_add3_u32 v74, v32, v74, s36
	v_add3_u32 v65, v65, v156, s36
	v_add3_u32 v67, v67, v158, s36
	v_bfe_u32 v77, v39, 16, 1
	v_bfe_u32 v79, v37, 16, 1
	v_bfe_u32 v82, v43, 16, 1
	v_bfe_u32 v86, v41, 16, 1
	v_bfe_u32 v90, v47, 16, 1
	v_bfe_u32 v94, v45, 16, 1
	v_and_or_b32 v50, v85, s37, v50
	v_and_or_b32 v51, v87, s37, v51
	v_and_or_b32 v52, v89, s37, v52
	v_and_or_b32 v53, v91, s37, v53
	v_and_or_b32 v54, v93, s37, v54
	v_and_or_b32 v55, v95, s37, v55
	v_lshrrev_b32_e32 v60, 16, v60
	v_lshrrev_b32_e32 v62, 16, v62
	v_lshrrev_b32_e32 v68, 16, v68
	v_lshrrev_b32_e32 v70, 16, v70
	v_lshrrev_b32_e32 v64, 16, v64
	v_lshrrev_b32_e32 v66, 16, v66
	v_add3_u32 v73, v35, v73, s36
	v_add3_u32 v75, v33, v75, s36
	v_add3_u32 v76, v38, v76, s36
	v_add3_u32 v78, v36, v78, s36
	v_add3_u32 v42, v42, v80, s36
	v_add3_u32 v40, v40, v84, s36
	v_add3_u32 v46, v46, v88, s36
	v_add3_u32 v44, v44, v92, s36
	global_store_dwordx2 v[132:133], v[48:49], off sc1
	global_store_dwordx2 v[132:133], v[50:51], off offset:512 sc1
	global_store_dwordx2 v[132:133], v[52:53], off offset:1024 sc1
	global_store_dwordx2 v[132:133], v[54:55], off offset:1536 sc1
	v_and_or_b32 v32, v57, s37, v56
	v_and_or_b32 v33, v59, s37, v58
	v_lshrrev_b32_e32 v48, 16, v72
	v_lshrrev_b32_e32 v49, 16, v74
	v_lshl_add_u64 v[108:109], v[108:109], 0, s[78:79]
	v_add3_u32 v77, v39, v77, s36
	v_add3_u32 v79, v37, v79, s36
	v_add3_u32 v43, v43, v82, s36
	v_add3_u32 v41, v41, v86, s36
	v_add3_u32 v47, v47, v90, s36
	v_add3_u32 v45, v45, v94, s36
	v_and_or_b32 v34, v61, s37, v60
	v_and_or_b32 v35, v63, s37, v62
	v_and_or_b32 v36, v69, s37, v68
	v_and_or_b32 v37, v71, s37, v70
	v_and_or_b32 v38, v65, s37, v64
	v_and_or_b32 v39, v67, s37, v66
	v_lshrrev_b32_e32 v50, 16, v76
	v_lshrrev_b32_e32 v51, 16, v78
	v_lshrrev_b32_e32 v42, 16, v42
	v_lshrrev_b32_e32 v40, 16, v40
	v_lshrrev_b32_e32 v46, 16, v46
	v_lshrrev_b32_e32 v44, 16, v44
	global_store_dwordx2 v[130:131], v[32:33], off sc1
	global_store_dwordx2 v[130:131], v[34:35], off offset:512 sc1
	global_store_dwordx2 v[130:131], v[36:37], off offset:1024 sc1
	global_store_dwordx2 v[130:131], v[38:39], off offset:1536 sc1
	v_and_or_b32 v32, v73, s37, v48
	v_and_or_b32 v33, v75, s37, v49
	v_and_or_b32 v34, v77, s37, v50
	v_and_or_b32 v35, v79, s37, v51
	v_and_or_b32 v36, v43, s37, v42
	v_and_or_b32 v37, v41, s37, v40
	v_and_or_b32 v38, v47, s37, v46
	v_and_or_b32 v39, v45, s37, v44
	global_store_dwordx2 v[128:129], v[32:33], off sc1
	global_store_dwordx2 v[128:129], v[34:35], off offset:512 sc1
	global_store_dwordx2 v[128:129], v[36:37], off offset:1024 sc1
	global_store_dwordx2 v[128:129], v[38:39], off offset:1536 sc1
	s_cbranch_scc1 .LBB0_51
	s_add_i32 s54, s54, s58
	v_lshl_add_u64 v[104:105], v[104:105], 0, s[60:61]
	s_cmp_lt_i32 s54, 0x8000
	v_lshl_add_u64 v[106:107], v[106:107], 0, s[72:73]
	s_cbranch_scc1 .LBB0_50

; template <int MODE, bool XB> __device__ __forceinline__ void norm_pass(const void* __restrict__ X, const float* __restrict__ g, const float* __restrict__ shift, const float* __restrict__ scale, ...
;     ...
;         for (int r = 0; r < 16; ++r) {
;             f32x4 v[4]; float s = 0.f;
; #pragma unroll
;             for (int j = 0; j < 4; ++j) {
;                 if constexpr (XB) { const v2u w = *(const v2u*)((const bf16*)X + (size_t)(m0 + r) * D + 4 * lane + 256 * j);
;                     v[j] = (f32x4){__uint_as_float(w.x << 16), __uint_as_float(w.x & 0xffff0000u), __uint_as_float(w.y << 16), __uint_as_float(w.y & 0xffff0000u)}; }
;                 else v[j] = *(const f32x4*)((const float*)X + (size_t)(m0 + r) * D + 4 * lane + 256 * j);
;                 s += (v[j][0] * v[j][0] + v[j][1] * v[j][1]) + (v[j][2] * v[j][2] + v[j][3] * v[j][3]); }
.LBB0_418:
	v_lshl_add_u64 v[58:59], v[40:41], 0, s[44:45]
	s_add_i32 s4, s50, -2
	s_add_i32 s6, s50, -1
	v_add_co_u32_e64 v60, s[0:1], s18, v58
	s_ashr_i32 s5, s4, 31
	s_ashr_i32 s51, s50, 31
	v_add_co_u32_e32 v62, vcc, 0x13000000, v58
	v_addc_co_u32_e64 v61, s[0:1], 0, v59, s[0:1]
	s_ashr_i32 s7, s6, 31
	s_lshl_b64 s[4:5], s[4:5], 11
	s_lshl_b64 s[0:1], s[50:51], 11
	v_addc_co_u32_e32 v63, vcc, 0, v59, vcc
	s_lshl_b64 s[6:7], s[6:7], 11
	v_lshl_add_u64 v[82:83], v[32:33], 0, s[4:5]
	v_lshl_add_u64 v[64:65], v[32:33], 0, s[0:1]
	global_load_dwordx2 v[66:67], v[62:63], off
	global_load_dwordx2 v[68:69], v[62:63], off offset:512
	global_load_dwordx2 v[70:71], v[62:63], off offset:1024
	global_load_dwordx2 v[72:73], v[62:63], off offset:1536
	global_load_dwordx2 v[74:75], v[64:65], off
	global_load_dwordx2 v[76:77], v[64:65], off offset:512
	global_load_dwordx2 v[78:79], v[64:65], off offset:1024
	global_load_dwordx2 v[80:81], v[64:65], off offset:1536
	v_lshl_add_u64 v[84:85], v[32:33], 0, s[6:7]
	global_load_dwordx2 v[92:93], v[82:83], off
	global_load_dwordx2 v[98:99], v[82:83], off offset:512
	global_load_dwordx2 v[100:101], v[82:83], off offset:1024
	global_load_dwordx2 v[102:103], v[82:83], off offset:1536
	global_load_dwordx2 v[104:105], v[84:85], off
	global_load_dwordx2 v[106:107], v[84:85], off offset:512
	global_load_dwordx2 v[108:109], v[84:85], off offset:1024
	global_load_dwordx2 v[126:127], v[84:85], off offset:1536
	v_lshl_add_u64 v[58:59], v[34:35], 0, s[0:1]
	v_lshl_add_u64 v[64:65], v[34:35], 0, s[4:5]
	v_lshl_add_u64 v[62:63], v[34:35], 0, s[6:7]
	s_add_i32 s50, s50, 4
	s_add_u32 s44, s44, 0x2000
	s_addc_u32 s45, s45, 0
	s_cmpk_lg_u32 s44, 0x8000
	s_waitcnt vmcnt(15)
	v_and_b32_e32 v83, 0xffff0000, v66
	v_and_b32_e32 v85, 0xffff0000, v67
	v_lshlrev_b32_e32 v82, 16, v66
	v_lshlrev_b32_e32 v84, 16, v67
	s_waitcnt vmcnt(14)
	v_lshlrev_b32_e32 v129, 16, v69
	v_and_b32_e32 v87, 0xffff0000, v69
	v_and_b32_e32 v86, 0xffff0000, v68
	s_waitcnt vmcnt(13)
	v_lshlrev_b32_e32 v88, 16, v70
	v_and_b32_e32 v89, 0xffff0000, v70
	v_lshlrev_b32_e32 v90, 16, v71
	v_and_b32_e32 v91, 0xffff0000, v71
	s_waitcnt vmcnt(12)
	v_lshlrev_b32_e32 v141, 16, v72
	s_waitcnt vmcnt(11)
	v_and_b32_e32 v67, 0xffff0000, v74
	v_and_b32_e32 v69, 0xffff0000, v75
	s_waitcnt vmcnt(10)
	v_and_b32_e32 v71, 0xffff0000, v77
	v_and_b32_e32 v70, 0xffff0000, v76
	v_mul_f32_e32 v122, v85, v85
	v_mul_f32_e32 v140, v83, v83
	s_waitcnt vmcnt(4)
	v_and_b32_e32 v123, 0xffff0000, v102
	v_lshlrev_b32_e32 v128, 16, v68
	v_lshlrev_b32_e32 v94, 16, v73
	v_and_b32_e32 v95, 0xffff0000, v73
	v_lshlrev_b32_e32 v66, 16, v74
	v_lshlrev_b32_e32 v68, 16, v75
	v_lshlrev_b32_e32 v143, 16, v77
	v_lshlrev_b32_e32 v142, 16, v76
	v_and_b32_e32 v73, 0xffff0000, v78
	v_lshlrev_b32_e32 v145, 16, v80
	v_pk_mul_f32 v[146:147], v[86:87], v[86:87]
	v_mov_b32_e32 v149, v141
	v_mul_f32_e32 v144, v89, v89
	v_mul_f32_e32 v148, v91, v91
	v_and_b32_e32 v111, 0xffff0000, v92
	v_lshlrev_b32_e32 v112, 16, v93
	v_and_b32_e32 v113, 0xffff0000, v93
	v_lshlrev_b32_e32 v151, 16, v99
	v_and_b32_e32 v115, 0xffff0000, v99
	v_and_b32_e32 v114, 0xffff0000, v98
	v_lshlrev_b32_e32 v116, 16, v100
	v_and_b32_e32 v117, 0xffff0000, v100
	v_lshlrev_b32_e32 v118, 16, v101
	v_and_b32_e32 v119, 0xffff0000, v101
	v_lshlrev_b32_e32 v153, 16, v102
	s_waitcnt vmcnt(3)
	v_and_b32_e32 v93, 0xffff0000, v104
	v_and_b32_e32 v99, 0xffff0000, v105
	s_waitcnt vmcnt(2)
	v_and_b32_e32 v101, 0xffff0000, v107
	v_and_b32_e32 v100, 0xffff0000, v106
	s_waitcnt vmcnt(0)
	v_lshlrev_b32_e32 v157, 16, v126
	v_mul_f32_e32 v152, v69, v69
	v_pk_mul_f32 v[158:159], v[70:71], v[70:71]
	v_mul_f32_e32 v156, v67, v67
	v_pk_fma_f32 v[164:165], v[84:85], v[84:85], v[122:123] op_sel_hi:[1,1,0]
	v_pk_fma_f32 v[166:167], v[82:83], v[82:83], v[140:141] op_sel_hi:[1,1,0]
	v_and_b32_e32 v97, 0xffff0000, v72
	v_lshlrev_b32_e32 v72, 16, v78
	v_lshlrev_b32_e32 v74, 16, v79
	v_and_b32_e32 v75, 0xffff0000, v79
	v_and_b32_e32 v79, 0xffff0000, v80
	v_lshlrev_b32_e32 v76, 16, v81
	v_and_b32_e32 v77, 0xffff0000, v81
	v_lshlrev_b32_e32 v110, 16, v92
	v_lshlrev_b32_e32 v150, 16, v98
	v_lshlrev_b32_e32 v92, 16, v104
	v_lshlrev_b32_e32 v98, 16, v105
	v_lshlrev_b32_e32 v155, 16, v107
	v_lshlrev_b32_e32 v154, 16, v106
	v_mov_b32_e32 v161, v145
	v_mul_f32_e32 v160, v73, v73
	v_mov_b32_e32 v80, v142
	v_mov_b32_e32 v81, v70
	v_mov_b32_e32 v70, v143
	v_pk_fma_f32 v[146:147], v[128:129], v[128:129], v[146:147]
	v_pk_fma_f32 v[168:169], v[88:89], v[88:89], v[144:145] op_sel_hi:[1,1,0]
	v_pk_fma_f32 v[170:171], v[90:91], v[90:91], v[148:149] op_sel_hi:[1,1,0]
	v_mul_f32_e32 v144, v113, v113
	v_pk_mul_f32 v[172:173], v[114:115], v[114:115]
	v_mul_f32_e32 v174, v111, v111
	v_mul_f32_e32 v180, v99, v99
	v_pk_mul_f32 v[182:183], v[100:101], v[100:101]
	v_mul_f32_e32 v184, v93, v93
	v_mov_b32_e32 v175, v157
	v_pk_fma_f32 v[194:195], v[68:69], v[68:69], v[152:153] op_sel_hi:[1,1,0]
	v_pk_fma_f32 v[142:143], v[142:143], v[142:143], v[158:159]
	v_pk_fma_f32 v[158:159], v[66:67], v[66:67], v[156:157] op_sel_hi:[1,1,0]
	v_mov_b32_e32 v140, v166
	v_mov_b32_e32 v148, v164
	v_mul_f32_e32 v139, v97, v97
	v_mul_f32_e32 v177, v94, v94
	v_mul_f32_e32 v179, v95, v95
	v_mov_b32_e32 v124, v128
	v_mov_b32_e32 v125, v86
	v_mov_b32_e32 v86, v129
	v_mov_b32_e32 v96, v141
	v_lshlrev_b32_e32 v120, 16, v103
	v_and_b32_e32 v121, 0xffff0000, v103
	v_and_b32_e32 v103, 0xffff0000, v108
	v_lshlrev_b32_e32 v104, 16, v109
	v_and_b32_e32 v105, 0xffff0000, v109
	v_and_b32_e32 v109, 0xffff0000, v126
	v_lshlrev_b32_e32 v106, 16, v127
	v_and_b32_e32 v107, 0xffff0000, v127
	v_mul_f32_e32 v162, v75, v75
	v_mov_b32_e32 v163, v153
; template <int MODE, bool XB> __device__ __forceinline__ void norm_pass(const void* __restrict__ X, const float* __restrict__ g, const float* __restrict__ shift, const float* __restrict__ scale, ...
;     ...
;                 if constexpr (XB) { const v2u w = *(const v2u*)((const bf16*)X + (size_t)(m0 + r) * D + 4 * lane + 256 * j);
;                     v[j] = (f32x4){__uint_as_float(w.x << 16), __uint_as_float(w.x & 0xffff0000u), __uint_as_float(w.y << 16), __uint_as_float(w.y & 0xffff0000u)}; }
;                 else v[j] = *(const f32x4*)((const float*)X + (size_t)(m0 + r) * D + 4 * lane + 256 * j);
;                 s += (v[j][0] * v[j][0] + v[j][1] * v[j][1]) + (v[j][2] * v[j][2] + v[j][3] * v[j][3]); }
;             const float rstd = 1.0f / sqrtf(wave_sum(s) * (1.f / D) + 1e-6f);
	v_mov_b32_e32 v128, v150
	v_mov_b32_e32 v129, v114
	v_mov_b32_e32 v114, v151
	v_mov_b32_e32 v126, v154
	v_mov_b32_e32 v127, v100
	v_mov_b32_e32 v100, v155
	v_pk_fma_f32 v[196:197], v[72:73], v[72:73], v[160:161] op_sel_hi:[1,1,0]
	v_pk_add_f32 v[164:165], v[166:167], v[164:165]
	v_pk_add_f32 v[146:147], v[146:147], v[146:147] op_sel:[0,1] op_sel_hi:[1,0]
	v_pk_fma_f32 v[166:167], v[112:113], v[112:113], v[144:145] op_sel_hi:[1,1,0]
	v_pk_fma_f32 v[150:151], v[150:151], v[150:151], v[172:173]
	v_pk_fma_f32 v[172:173], v[110:111], v[110:111], v[174:175] op_sel_hi:[1,1,0]
	v_pk_fma_f32 v[180:181], v[98:99], v[98:99], v[180:181] op_sel_hi:[1,1,0]
	v_pk_fma_f32 v[154:155], v[154:155], v[154:155], v[182:183]
	v_pk_fma_f32 v[182:183], v[92:93], v[92:93], v[184:185] op_sel_hi:[1,1,0]
	v_mov_b32_e32 v144, v158
	v_mov_b32_e32 v160, v194
	v_pk_mul_f32 v[140:141], v[140:141], v[148:149]
	v_lshlrev_b32_e32 v102, 16, v108
	v_mul_f32_e32 v186, v79, v79
	v_mul_f32_e32 v187, v76, v76
	v_mul_f32_e32 v193, v77, v77
	v_mov_b32_e32 v78, v145
	v_mul_f32_e32 v176, v117, v117
	v_mul_f32_e32 v178, v119, v119
	v_mul_f32_e32 v190, v103, v103
	v_mul_f32_e32 v192, v105, v105
	v_pk_fma_f32 v[198:199], v[74:75], v[74:75], v[162:163] op_sel_hi:[1,1,0]
	v_mov_b32_e32 v169, v177
	v_mov_b32_e32 v171, v179
	v_pk_add_f32 v[158:159], v[158:159], v[194:195]
	v_pk_add_f32 v[142:143], v[142:143], v[142:143] op_sel:[0,1] op_sel_hi:[1,0]
	v_mov_b32_e32 v147, v139
	v_mov_b32_e32 v152, v172
	v_mov_b32_e32 v162, v166
	v_mov_b32_e32 v156, v182
	v_mov_b32_e32 v174, v180
	v_pk_mul_f32 v[144:145], v[144:145], v[160:161]
	v_mov_b32_e32 v165, v141
	v_mul_f32_e32 v200, v123, v123
	v_mul_f32_e32 v201, v120, v120
	v_mul_f32_e32 v202, v121, v121
	v_mul_f32_e32 v203, v109, v109
	v_mul_f32_e32 v204, v106, v106
	v_mul_f32_e32 v205, v107, v107
	v_mov_b32_e32 v108, v157
	v_pk_fma_f32 v[176:177], v[116:117], v[116:117], v[176:177] op_sel_hi:[1,1,0]
	v_pk_fma_f32 v[178:179], v[118:119], v[118:119], v[178:179] op_sel_hi:[1,1,0]
	v_pk_fma_f32 v[184:185], v[102:103], v[102:103], v[190:191] op_sel_hi:[1,1,0]
	v_pk_fma_f32 v[190:191], v[104:105], v[104:105], v[192:193] op_sel_hi:[1,1,0]
	v_mov_b32_e32 v197, v187
	v_mov_b32_e32 v199, v193
	v_pk_add_f32 v[148:149], v[168:169], v[170:171]
	v_pk_add_f32 v[166:167], v[172:173], v[166:167]
	v_pk_add_f32 v[150:151], v[150:151], v[150:151] op_sel:[0,1] op_sel_hi:[1,0]
	v_pk_add_f32 v[168:169], v[182:183], v[180:181]
	v_pk_add_f32 v[154:155], v[154:155], v[154:155] op_sel:[0,1] op_sel_hi:[1,0]
	v_mov_b32_e32 v143, v186
	v_pk_mul_f32 v[140:141], v[152:153], v[162:163]
	v_pk_mul_f32 v[156:157], v[156:157], v[174:175]
	v_mov_b32_e32 v159, v145
	v_pk_add_f32 v[144:145], v[164:165], v[146:147]
	v_mov_b32_e32 v177, v201
	v_mov_b32_e32 v179, v202
	v_mov_b32_e32 v185, v204
	v_mov_b32_e32 v191, v205
	v_pk_add_f32 v[160:161], v[196:197], v[198:199]
	v_mov_b32_e32 v151, v200
	v_mov_b32_e32 v155, v203
	v_mov_b32_e32 v167, v141
	v_mov_b32_e32 v169, v157
	v_pk_add_f32 v[140:141], v[158:159], v[142:143]
	v_pk_add_f32 v[142:143], v[144:145], v[148:149]
	v_mov_b32_e32 v122, v153
	v_pk_add_f32 v[152:153], v[176:177], v[178:179]
	v_pk_add_f32 v[162:163], v[184:185], v[190:191]
	v_pk_add_f32 v[144:145], v[166:167], v[150:151]
	v_pk_add_f32 v[146:147], v[168:169], v[154:155]
	v_pk_add_f32 v[140:141], v[140:141], v[160:161]
	v_add_f32_e32 v139, v142, v143
	v_pk_add_f32 v[142:143], v[144:145], v[152:153]
	v_pk_add_f32 v[144:145], v[146:147], v[162:163]
	v_add_f32_e32 v140, v140, v141
	ds_bpermute_b32 v141, v130, v139
	v_add_f32_e32 v142, v142, v143
	ds_bpermute_b32 v143, v130, v140
	v_add_f32_e32 v144, v144, v145
	ds_bpermute_b32 v145, v130, v142
	ds_bpermute_b32 v146, v130, v144
	s_waitcnt lgkmcnt(3)
	v_add_f32_e32 v139, v139, v141
	s_waitcnt lgkmcnt(2)
	v_add_f32_e32 v140, v140, v143
	ds_bpermute_b32 v141, v131, v139
	s_waitcnt lgkmcnt(2)
	v_add_f32_e32 v142, v142, v145
	ds_bpermute_b32 v143, v131, v140
	s_waitcnt lgkmcnt(2)
	v_add_f32_e32 v144, v144, v146
	ds_bpermute_b32 v145, v131, v142
	ds_bpermute_b32 v146, v131, v144
	s_waitcnt lgkmcnt(3)
	v_add_f32_e32 v139, v139, v141
	s_waitcnt lgkmcnt(2)
	v_add_f32_e32 v140, v140, v143
	ds_bpermute_b32 v141, v132, v139
	s_waitcnt lgkmcnt(2)
	v_add_f32_e32 v142, v142, v145
	ds_bpermute_b32 v143, v132, v140
	s_waitcnt lgkmcnt(2)
	v_add_f32_e32 v144, v144, v146
	ds_bpermute_b32 v145, v132, v142
	ds_bpermute_b32 v146, v132, v144
	s_waitcnt lgkmcnt(3)
	v_add_f32_e32 v139, v139, v141
	s_waitcnt lgkmcnt(2)
	v_add_f32_e32 v140, v140, v143
	ds_bpermute_b32 v141, v133, v139
	s_waitcnt lgkmcnt(2)
	v_add_f32_e32 v142, v142, v145
	ds_bpermute_b32 v143, v133, v140
	s_waitcnt lgkmcnt(2)
	v_add_f32_e32 v144, v144, v146
	ds_bpermute_b32 v145, v133, v142
	ds_bpermute_b32 v146, v133, v144
	s_waitcnt lgkmcnt(3)
	v_add_f32_e32 v139, v139, v141
	s_waitcnt lgkmcnt(2)
	v_add_f32_e32 v140, v140, v143
	ds_bpermute_b32 v141, v134, v139
	s_waitcnt lgkmcnt(2)
	v_add_f32_e32 v142, v142, v145
	ds_bpermute_b32 v143, v134, v140
	s_waitcnt lgkmcnt(2)
	v_add_f32_e32 v144, v144, v146
	ds_bpermute_b32 v145, v134, v142
	ds_bpermute_b32 v146, v134, v144
	s_waitcnt lgkmcnt(3)
	v_add_f32_e32 v139, v139, v141
	s_waitcnt lgkmcnt(2)
	v_add_f32_e32 v140, v140, v143
	ds_bpermute_b32 v141, v135, v139
	s_waitcnt lgkmcnt(2)
	v_add_f32_e32 v142, v142, v145
	ds_bpermute_b32 v143, v135, v140
	s_waitcnt lgkmcnt(2)
	v_add_f32_e32 v144, v144, v146
	ds_bpermute_b32 v145, v135, v142
	ds_bpermute_b32 v146, v135, v144
	s_waitcnt lgkmcnt(3)
	v_add_f32_e32 v139, v139, v141
	s_waitcnt lgkmcnt(2)
	v_add_f32_e32 v140, v140, v143
	v_fmamk_f32 v139, v139, 0x3a800000, v137
	s_waitcnt lgkmcnt(1)
; __device__ __forceinline__ unsigned pk2(float lo, float hi) { return f2bf(lo) | (f2bf(hi) << 16); }
; template <int MODE, bool XB> __device__ __forceinline__ void norm_pass(const void* __restrict__ X, const float* __restrict__ g, const float* __restrict__ shift, const float* __restrict__ scale, ...
;     ...
;             const float rstd = 1.0f / sqrtf(wave_sum(s) * (1.f / D) + 1e-6f);
; #pragma unroll
;             for (int j = 0; j < 4; ++j) {
;                 if (MODE == 0) { const f32x4 o = v[j] * rstd * gm[j] + sh[j]; v2u w; w.x = pk2(o[0], o[1]); w.y = pk2(o[2], o[3]); *(v2u*)(Hb + (size_t)(m0 + r) * D + 4 * lane + 256 * j) = w; }
	v_add_f32_e32 v141, v142, v145
	s_waitcnt lgkmcnt(0)
	v_add_f32_e32 v142, v144, v146
	v_fmamk_f32 v140, v140, 0x3a800000, v137
	v_mul_f32_e32 v143, 0x4f800000, v139
	v_cmp_gt_f32_e64 s[0:1], s12, v139
	v_fmamk_f32 v141, v141, 0x3a800000, v137
	v_fmamk_f32 v142, v142, 0x3a800000, v137
	v_mul_f32_e32 v144, 0x4f800000, v140
	v_cmp_gt_f32_e32 vcc, s12, v140
	v_cndmask_b32_e64 v139, v139, v143, s[0:1]
	v_mul_f32_e32 v143, 0x4f800000, v141
	v_cmp_gt_f32_e64 s[4:5], s12, v141
	v_mul_f32_e32 v145, 0x4f800000, v142
	v_cmp_gt_f32_e64 s[6:7], s12, v142
	v_cndmask_b32_e32 v140, v140, v144, vcc
	v_sqrt_f32_e32 v144, v139
	v_cndmask_b32_e64 v141, v141, v143, s[4:5]
	v_cndmask_b32_e64 v142, v142, v145, s[6:7]
	v_sqrt_f32_e32 v143, v140
	v_sqrt_f32_e32 v145, v141
	v_sqrt_f32_e32 v146, v142
	v_add_u32_e32 v147, -1, v144
	v_add_u32_e32 v148, 1, v144
	v_add_u32_e32 v149, -1, v143
	v_fma_f32 v151, -v147, v144, v139
	v_add_u32_e32 v150, 1, v143
	v_fma_f32 v152, -v148, v144, v139
	v_add_u32_e32 v153, -1, v145
	v_add_u32_e32 v155, -1, v146
	v_fma_f32 v157, -v149, v143, v140
	v_cmp_ge_f32_e64 s[10:11], 0, v151
	v_add_u32_e32 v154, 1, v145
	v_add_u32_e32 v156, 1, v146
	v_fma_f32 v158, -v150, v143, v140
	v_cndmask_b32_e64 v144, v144, v147, s[10:11]
	v_fma_f32 v147, -v153, v145, v141
	v_fma_f32 v159, -v155, v146, v142
	v_cmp_ge_f32_e64 s[10:11], 0, v157
	v_cmp_lt_f32_e64 s[14:15], 0, v152
	v_fma_f32 v151, -v154, v145, v141
	v_fma_f32 v160, -v156, v146, v142
	v_cndmask_b32_e64 v143, v143, v149, s[10:11]
	v_cmp_lt_f32_e64 s[10:11], 0, v158
	v_cndmask_b32_e64 v144, v144, v148, s[14:15]
	v_cmp_ge_f32_e64 s[14:15], 0, v147
	v_cmp_ge_f32_e64 s[16:17], 0, v159
	v_cndmask_b32_e64 v143, v143, v150, s[10:11]
	v_cndmask_b32_e64 v145, v145, v153, s[14:15]
	v_cmp_lt_f32_e64 s[14:15], 0, v151
	v_cndmask_b32_e64 v146, v146, v155, s[16:17]
	v_cmp_lt_f32_e64 s[16:17], 0, v160
	v_mul_f32_e32 v147, 0x37800000, v144
	v_cndmask_b32_e64 v145, v145, v154, s[14:15]
	v_cndmask_b32_e64 v146, v146, v156, s[16:17]
	v_mul_f32_e32 v148, 0x37800000, v143
	v_cndmask_b32_e64 v144, v144, v147, s[0:1]
	v_cmp_class_f32_e64 s[0:1], v139, v138
	v_mul_f32_e32 v147, 0x37800000, v145
	v_mul_f32_e32 v149, 0x37800000, v146
	v_cndmask_b32_e32 v143, v143, v148, vcc
	v_cmp_class_f32_e32 vcc, v140, v138
	v_cndmask_b32_e64 v139, v144, v139, s[0:1]
	v_cndmask_b32_e64 v144, v145, v147, s[4:5]
	v_cmp_class_f32_e64 s[0:1], v141, v138
	v_cndmask_b32_e64 v145, v146, v149, s[6:7]
	v_cmp_class_f32_e64 s[4:5], v142, v138
	v_cndmask_b32_e32 v143, v143, v140, vcc
	v_div_scale_f32 v140, s[6:7], v139, v139, 1.0
	v_cndmask_b32_e64 v141, v144, v141, s[0:1]
	v_cndmask_b32_e64 v142, v145, v142, s[4:5]
	v_div_scale_f32 v144, s[0:1], v143, v143, 1.0
	v_rcp_f32_e32 v147, v140
	v_div_scale_f32 v148, s[4:5], v141, v141, 1.0
	v_div_scale_f32 v150, s[6:7], v142, v142, 1.0
	v_rcp_f32_e32 v152, v144
	v_rcp_f32_e32 v153, v148
	v_rcp_f32_e32 v154, v150
	v_fma_f32 v155, -v140, v147, 1.0
	v_div_scale_f32 v146, vcc, 1.0, v139, 1.0
	v_fma_f32 v156, -v144, v152, 1.0
	v_fmac_f32_e32 v147, v155, v147
	v_fma_f32 v155, -v148, v153, 1.0
	v_fma_f32 v157, -v150, v154, 1.0
	v_fmac_f32_e32 v152, v156, v152
	v_mul_f32_e32 v156, v146, v147
	v_div_scale_f32 v145, s[0:1], 1.0, v143, 1.0
	v_div_scale_f32 v149, s[4:5], 1.0, v141, 1.0
	v_fmac_f32_e32 v153, v155, v153
	v_fmac_f32_e32 v154, v157, v154
	v_fma_f32 v157, -v140, v156, v146
	v_div_scale_f32 v151, s[6:7], 1.0, v142, 1.0
	v_mul_f32_e32 v155, v145, v152
	v_mul_f32_e32 v158, v149, v153
	v_fmac_f32_e32 v156, v157, v147
	v_mul_f32_e32 v159, v151, v154
	v_fma_f32 v160, -v144, v155, v145
	v_fma_f32 v157, -v148, v158, v149
	v_fma_f32 v140, -v140, v156, v146
	v_fma_f32 v161, -v150, v159, v151
	v_fmac_f32_e32 v155, v160, v152
	v_fmac_f32_e32 v158, v157, v153
	v_div_fmas_f32 v140, v140, v147, v156
	v_fmac_f32_e32 v159, v161, v154
	v_fma_f32 v144, -v144, v155, v145
	v_fma_f32 v145, -v148, v158, v149
	v_div_fixup_f32 v140, v140, v139, 1.0
	s_mov_b64 vcc, s[4:5]
	v_fma_f32 v146, -v150, v159, v151
	v_div_fmas_f32 v139, v145, v153, v158
	v_pk_mul_f32 v[82:83], v[140:141], v[82:83] op_sel_hi:[0,1]
	s_mov_b64 vcc, s[6:7]
	v_pk_mul_f32 v[84:85], v[140:141], v[84:85] op_sel_hi:[0,1]
	v_pk_mul_f32 v[124:125], v[140:141], v[124:125] op_sel_hi:[0,1]
	v_pk_mul_f32 v[86:87], v[140:141], v[86:87] op_sel_hi:[0,1]
	v_pk_mul_f32 v[88:89], v[140:141], v[88:89] op_sel_hi:[0,1]
	v_pk_mul_f32 v[90:91], v[140:141], v[90:91] op_sel_hi:[0,1]
	v_pk_mul_f32 v[96:97], v[96:97], v[140:141] op_sel_hi:[1,0]
	v_pk_mul_f32 v[94:95], v[94:95], v[140:141] op_sel_hi:[1,0]
	v_div_fixup_f32 v140, v139, v141, 1.0
	v_div_fmas_f32 v139, v146, v154, v159
	v_pk_fma_f32 v[82:83], v[44:45], v[82:83], v[16:17]
	s_mov_b64 vcc, s[0:1]
	v_pk_fma_f32 v[84:85], v[42:43], v[84:85], v[18:19]
	v_pk_fma_f32 v[86:87], v[46:47], v[86:87], v[22:23]
	v_pk_fma_f32 v[124:125], v[48:49], v[124:125], v[20:21]
	v_pk_fma_f32 v[90:91], v[50:51], v[90:91], v[26:27]
	v_pk_fma_f32 v[88:89], v[52:53], v[88:89], v[24:25]
	v_pk_fma_f32 v[94:95], v[54:55], v[94:95], v[30:31]
	v_pk_fma_f32 v[96:97], v[56:57], v[96:97], v[28:29]
	v_pk_mul_f32 v[110:111], v[140:141], v[110:111] op_sel_hi:[0,1]
	v_pk_mul_f32 v[112:113], v[140:141], v[112:113] op_sel_hi:[0,1]
	v_pk_mul_f32 v[128:129], v[140:141], v[128:129] op_sel_hi:[0,1]
	v_pk_mul_f32 v[114:115], v[140:141], v[114:115] op_sel_hi:[0,1]
	v_pk_mul_f32 v[116:117], v[140:141], v[116:117] op_sel_hi:[0,1]
	v_pk_mul_f32 v[118:119], v[140:141], v[118:119] op_sel_hi:[0,1]
	v_pk_mul_f32 v[122:123], v[122:123], v[140:141] op_sel_hi:[1,0]
	v_pk_mul_f32 v[120:121], v[120:121], v[140:141] op_sel_hi:[1,0]
	v_div_fixup_f32 v140, v139, v142, 1.0
; __device__ __forceinline__ unsigned pk2(float lo, float hi) { return f2bf(lo) | (f2bf(hi) << 16); }
; template <int MODE, bool XB> __device__ __forceinline__ void norm_pass(const void* __restrict__ X, const float* __restrict__ g, const float* __restrict__ shift, const float* __restrict__ scale, ...
;     ...
;             for (int j = 0; j < 4; ++j) {
;                 if (MODE == 0) { const f32x4 o = v[j] * rstd * gm[j] + sh[j]; v2u w; w.x = pk2(o[0], o[1]); w.y = pk2(o[2], o[3]); *(v2u*)(Hb + (size_t)(m0 + r) * D + 4 * lane + 256 * j) = w; }
	v_div_fmas_f32 v139, v144, v152, v155
	v_bfe_u32 v141, v82, 16, 1
	v_bfe_u32 v142, v83, 16, 1
	v_bfe_u32 v144, v84, 16, 1
	v_bfe_u32 v145, v85, 16, 1
	v_bfe_u32 v146, v124, 16, 1
	v_bfe_u32 v147, v125, 16, 1
	v_bfe_u32 v148, v86, 16, 1
	v_bfe_u32 v149, v87, 16, 1
	v_bfe_u32 v150, v88, 16, 1
	v_bfe_u32 v151, v89, 16, 1
	v_bfe_u32 v152, v90, 16, 1
	v_bfe_u32 v154, v96, 16, 1
	v_bfe_u32 v156, v94, 16, 1
	v_pk_fma_f32 v[112:113], v[42:43], v[112:113], v[18:19]
	v_pk_fma_f32 v[110:111], v[44:45], v[110:111], v[16:17]
	v_pk_fma_f32 v[114:115], v[46:47], v[114:115], v[22:23]
	v_pk_fma_f32 v[128:129], v[48:49], v[128:129], v[20:21]
	v_pk_fma_f32 v[118:119], v[50:51], v[118:119], v[26:27]
	v_pk_fma_f32 v[116:117], v[52:53], v[116:117], v[24:25]
	v_pk_fma_f32 v[122:123], v[56:57], v[122:123], v[28:29]
	v_pk_mul_f32 v[92:93], v[140:141], v[92:93] op_sel_hi:[0,1]
	v_pk_mul_f32 v[98:99], v[140:141], v[98:99] op_sel_hi:[0,1]
	v_pk_mul_f32 v[126:127], v[140:141], v[126:127] op_sel_hi:[0,1]
	v_pk_mul_f32 v[100:101], v[140:141], v[100:101] op_sel_hi:[0,1]
	v_pk_mul_f32 v[102:103], v[140:141], v[102:103] op_sel_hi:[0,1]
	v_pk_mul_f32 v[104:105], v[140:141], v[104:105] op_sel_hi:[0,1]
	v_pk_mul_f32 v[108:109], v[108:109], v[140:141] op_sel_hi:[1,0]
	v_pk_mul_f32 v[106:107], v[106:107], v[140:141] op_sel_hi:[1,0]
	v_div_fixup_f32 v140, v139, v143, 1.0
	v_add3_u32 v139, v82, v141, s13
	v_add3_u32 v141, v83, v142, s13
	v_bfe_u32 v153, v91, 16, 1
	v_bfe_u32 v155, v97, 16, 1
	v_bfe_u32 v157, v95, 16, 1
	v_pk_fma_f32 v[120:121], v[54:55], v[120:121], v[30:31]
	v_add3_u32 v142, v84, v144, s13
	v_add3_u32 v143, v85, v145, s13
	v_add3_u32 v124, v124, v146, s13
	v_add3_u32 v125, v125, v147, s13
	v_add3_u32 v144, v86, v148, s13
	v_add3_u32 v145, v87, v149, s13
	v_add3_u32 v146, v88, v150, s13
	v_add3_u32 v147, v89, v151, s13
	v_add3_u32 v148, v90, v152, s13
	v_add3_u32 v150, v96, v154, s13
	v_add3_u32 v152, v94, v156, s13
	v_bfe_u32 v154, v110, 16, 1
	v_bfe_u32 v156, v112, 16, 1
	v_bfe_u32 v158, v128, 16, 1
	v_bfe_u32 v160, v114, 16, 1
	v_bfe_u32 v162, v116, 16, 1
	v_bfe_u32 v164, v118, 16, 1
	v_bfe_u32 v166, v122, 16, 1
	v_pk_fma_f32 v[82:83], v[42:43], v[98:99], v[18:19]
	v_pk_fma_f32 v[84:85], v[44:45], v[92:93], v[16:17]
	v_pk_fma_f32 v[86:87], v[46:47], v[100:101], v[22:23]
	v_pk_fma_f32 v[88:89], v[48:49], v[126:127], v[20:21]
	v_pk_mul_f32 v[66:67], v[140:141], v[66:67] op_sel_hi:[0,1]
	v_pk_mul_f32 v[68:69], v[140:141], v[68:69] op_sel_hi:[0,1]
	v_add3_u32 v149, v91, v153, s13
	v_add3_u32 v151, v97, v155, s13
	v_add3_u32 v153, v95, v157, s13
	v_bfe_u32 v155, v111, 16, 1
	v_bfe_u32 v157, v113, 16, 1
	v_bfe_u32 v159, v129, 16, 1
	v_bfe_u32 v161, v115, 16, 1
	v_bfe_u32 v163, v117, 16, 1
	v_bfe_u32 v165, v119, 16, 1
	v_bfe_u32 v167, v123, 16, 1
	v_bfe_u32 v168, v120, 16, 1
	v_pk_fma_f32 v[90:91], v[50:51], v[104:105], v[26:27]
	v_pk_fma_f32 v[92:93], v[52:53], v[102:103], v[24:25]
	v_pk_fma_f32 v[94:95], v[54:55], v[106:107], v[30:31]
	v_pk_fma_f32 v[96:97], v[56:57], v[108:109], v[28:29]
	v_pk_mul_f32 v[80:81], v[140:141], v[80:81] op_sel_hi:[0,1]
	v_pk_mul_f32 v[70:71], v[140:141], v[70:71] op_sel_hi:[0,1]
	v_pk_mul_f32 v[72:73], v[140:141], v[72:73] op_sel_hi:[0,1]
	v_pk_mul_f32 v[74:75], v[140:141], v[74:75] op_sel_hi:[0,1]
	v_pk_mul_f32 v[78:79], v[78:79], v[140:141] op_sel_hi:[1,0]
	v_pk_mul_f32 v[76:77], v[76:77], v[140:141] op_sel_hi:[1,0]
	v_lshrrev_b32_e32 v98, 16, v139
	v_lshrrev_b32_e32 v99, 16, v142
	v_lshrrev_b32_e32 v100, 16, v124
	v_lshrrev_b32_e32 v101, 16, v144
	v_lshrrev_b32_e32 v103, 16, v148
	v_add3_u32 v106, v110, v154, s13
	v_add3_u32 v108, v112, v156, s13
	v_add3_u32 v110, v128, v158, s13
	v_add3_u32 v112, v114, v160, s13
	v_add3_u32 v114, v116, v162, s13
	v_add3_u32 v116, v118, v164, s13
	v_add3_u32 v118, v122, v166, s13
	v_bfe_u32 v122, v84, 16, 1
	v_bfe_u32 v124, v82, 16, 1
	v_bfe_u32 v127, v88, 16, 1
	v_bfe_u32 v128, v89, 16, 1
	v_bfe_u32 v139, v87, 16, 1
	v_pk_fma_f32 v[68:69], v[42:43], v[68:69], v[18:19]
	v_pk_fma_f32 v[66:67], v[44:45], v[66:67], v[16:17]
	v_bfe_u32 v169, v121, 16, 1
	v_lshrrev_b32_e32 v102, 16, v146
	v_lshrrev_b32_e32 v104, 16, v150
	v_lshrrev_b32_e32 v105, 16, v152
	v_add3_u32 v107, v111, v155, s13
	v_add3_u32 v109, v113, v157, s13
	v_add3_u32 v111, v129, v159, s13
	v_add3_u32 v113, v115, v161, s13
	v_add3_u32 v115, v117, v163, s13
	v_add3_u32 v117, v119, v165, s13
	v_add3_u32 v119, v123, v167, s13
	v_add3_u32 v120, v120, v168, s13
	v_bfe_u32 v123, v85, 16, 1
	v_bfe_u32 v126, v83, 16, 1
	v_bfe_u32 v129, v86, 16, 1
	v_bfe_u32 v140, v92, 16, 1
	v_bfe_u32 v144, v90, 16, 1
	v_bfe_u32 v148, v96, 16, 1
	v_bfe_u32 v152, v94, 16, 1
	v_pk_fma_f32 v[70:71], v[46:47], v[70:71], v[22:23]
	v_pk_fma_f32 v[80:81], v[48:49], v[80:81], v[20:21]
	v_pk_fma_f32 v[74:75], v[50:51], v[74:75], v[26:27]
; __device__ __forceinline__ unsigned pk2(float lo, float hi) { return f2bf(lo) | (f2bf(hi) << 16); }
; template <int MODE, bool XB> __device__ __forceinline__ void norm_pass(const void* __restrict__ X, const float* __restrict__ g, const float* __restrict__ shift, const float* __restrict__ scale, ...
;     ...
;     for (int m0 = gw * 16; m0 < M; m0 += NGW * 16) {
;         const int b = m0 / SEQ;
;         f32x4 gm[4], sh[4];
; #pragma unroll
;         for (int j = 0; j < 4; ++j) { const int col = 4 * lane + 256 * j; gm[j] = *(const f32x4*)(g + col);
;             if (MODE == 0) { gm[j] = gm[j] * (*(const f32x4*)(scale + (size_t)b * NMOD9 + col) + 1.0f); sh[j] = *(const f32x4*)(shift + (size_t)b * NMOD9 + col); } }
; #pragma unroll 4
;         for (int r = 0; r < 16; ++r) {
;     ...
;             for (int j = 0; j < 4; ++j) {
;                 if (MODE == 0) { const f32x4 o = v[j] * rstd * gm[j] + sh[j]; v2u w; w.x = pk2(o[0], o[1]); w.y = pk2(o[2], o[3]); *(v2u*)(Hb + (size_t)(m0 + r) * D + 4 * lane + 256 * j) = w; }
	v_pk_fma_f32 v[72:73], v[52:53], v[72:73], v[24:25]
	v_pk_fma_f32 v[76:77], v[54:55], v[76:77], v[30:31]
	v_pk_fma_f32 v[78:79], v[56:57], v[78:79], v[28:29]
	v_and_or_b32 v98, v141, s9, v98
	v_and_or_b32 v99, v143, s9, v99
	v_and_or_b32 v101, v145, s9, v101
	v_and_or_b32 v103, v149, s9, v103
	v_lshrrev_b32_e32 v106, 16, v106
	v_lshrrev_b32_e32 v108, 16, v108
	v_lshrrev_b32_e32 v110, 16, v110
	v_lshrrev_b32_e32 v112, 16, v112
	v_add3_u32 v122, v84, v122, s13
	v_add3_u32 v124, v82, v124, s13
	v_add3_u32 v88, v88, v127, s13
	v_add3_u32 v89, v89, v128, s13
	v_add3_u32 v127, v87, v139, s13
	v_bfe_u32 v128, v66, 16, 1
	v_bfe_u32 v139, v68, 16, 1
	v_add3_u32 v121, v121, v169, s13
	v_bfe_u32 v142, v93, 16, 1
	v_bfe_u32 v146, v91, 16, 1
	v_bfe_u32 v150, v97, 16, 1
	v_bfe_u32 v154, v95, 16, 1
	v_and_or_b32 v100, v125, s9, v100
	v_and_or_b32 v102, v147, s9, v102
	v_and_or_b32 v104, v151, s9, v104
	v_and_or_b32 v105, v153, s9, v105
	v_lshrrev_b32_e32 v114, 16, v114
	v_lshrrev_b32_e32 v116, 16, v116
	v_lshrrev_b32_e32 v118, 16, v118
	v_lshrrev_b32_e32 v120, 16, v120
	v_add3_u32 v123, v85, v123, s13
	v_add3_u32 v125, v83, v126, s13
	v_add3_u32 v126, v86, v129, s13
	v_add3_u32 v92, v92, v140, s13
	v_add3_u32 v90, v90, v144, s13
	v_add3_u32 v96, v96, v148, s13
	v_add3_u32 v94, v94, v152, s13
	v_bfe_u32 v129, v67, 16, 1
	v_bfe_u32 v140, v69, 16, 1
	v_bfe_u32 v141, v80, 16, 1
	v_bfe_u32 v143, v70, 16, 1
	v_bfe_u32 v145, v72, 16, 1
	v_bfe_u32 v147, v74, 16, 1
	v_bfe_u32 v149, v78, 16, 1
	v_bfe_u32 v151, v76, 16, 1
	global_store_dwordx2 v[60:61], v[98:99], off sc1
	global_store_dwordx2 v[60:61], v[100:101], off offset:512 sc1
	global_store_dwordx2 v[60:61], v[102:103], off offset:1024 sc1
	global_store_dwordx2 v[60:61], v[104:105], off offset:1536 sc1
	v_and_or_b32 v60, v107, s9, v106
	v_and_or_b32 v61, v109, s9, v108
	v_and_or_b32 v82, v111, s9, v110
	v_and_or_b32 v83, v113, s9, v112
	v_lshrrev_b32_e32 v98, 16, v122
	v_lshrrev_b32_e32 v99, 16, v124
	v_add3_u32 v101, v66, v128, s13
	v_add3_u32 v103, v68, v139, s13
	v_add3_u32 v93, v93, v142, s13
	v_add3_u32 v91, v91, v146, s13
	v_add3_u32 v97, v97, v150, s13
	v_add3_u32 v95, v95, v154, s13
	v_bfe_u32 v142, v81, 16, 1
	v_bfe_u32 v144, v71, 16, 1
	v_bfe_u32 v146, v73, 16, 1
	v_bfe_u32 v148, v75, 16, 1
	v_bfe_u32 v150, v79, 16, 1
	v_bfe_u32 v152, v77, 16, 1
	v_and_or_b32 v84, v115, s9, v114
	v_and_or_b32 v85, v117, s9, v116
	v_and_or_b32 v86, v119, s9, v118
	v_and_or_b32 v87, v121, s9, v120
	v_lshrrev_b32_e32 v88, 16, v88
	v_lshrrev_b32_e32 v100, 16, v126
	v_lshrrev_b32_e32 v92, 16, v92
	v_lshrrev_b32_e32 v90, 16, v90
	v_lshrrev_b32_e32 v96, 16, v96
	v_lshrrev_b32_e32 v94, 16, v94
	v_add3_u32 v102, v67, v129, s13
	v_add3_u32 v104, v69, v140, s13
	v_add3_u32 v80, v80, v141, s13
	v_add3_u32 v70, v70, v143, s13
	v_add3_u32 v72, v72, v145, s13
	v_add3_u32 v74, v74, v147, s13
	v_add3_u32 v78, v78, v149, s13
	v_add3_u32 v76, v76, v151, s13
	global_store_dwordx2 v[64:65], v[60:61], off sc1
	global_store_dwordx2 v[64:65], v[82:83], off offset:512 sc1
	global_store_dwordx2 v[64:65], v[84:85], off offset:1024 sc1
	global_store_dwordx2 v[64:65], v[86:87], off offset:1536 sc1
	v_and_or_b32 v60, v123, s9, v98
	v_and_or_b32 v61, v125, s9, v99
	v_lshrrev_b32_e32 v82, 16, v101
	v_lshrrev_b32_e32 v83, 16, v103
	v_add3_u32 v81, v81, v142, s13
	v_add3_u32 v71, v71, v144, s13
	v_add3_u32 v73, v73, v146, s13
	v_add3_u32 v75, v75, v148, s13
	v_add3_u32 v79, v79, v150, s13
	v_add3_u32 v77, v77, v152, s13
	v_and_or_b32 v64, v89, s9, v88
	v_and_or_b32 v65, v127, s9, v100
	v_and_or_b32 v66, v93, s9, v92
	v_and_or_b32 v67, v91, s9, v90
	v_and_or_b32 v68, v97, s9, v96
	v_and_or_b32 v69, v95, s9, v94
	v_lshrrev_b32_e32 v80, 16, v80
	v_lshrrev_b32_e32 v70, 16, v70
	v_lshrrev_b32_e32 v72, 16, v72
	v_lshrrev_b32_e32 v74, 16, v74
	v_lshrrev_b32_e32 v78, 16, v78
	v_lshrrev_b32_e32 v76, 16, v76
	global_store_dwordx2 v[62:63], v[60:61], off sc1
	global_store_dwordx2 v[62:63], v[64:65], off offset:512 sc1
	global_store_dwordx2 v[62:63], v[66:67], off offset:1024 sc1
	global_store_dwordx2 v[62:63], v[68:69], off offset:1536 sc1
	v_and_or_b32 v60, v102, s9, v82
	v_and_or_b32 v61, v104, s9, v83
	v_and_or_b32 v62, v81, s9, v80
	v_and_or_b32 v63, v71, s9, v70
	v_and_or_b32 v64, v73, s9, v72
	v_and_or_b32 v65, v75, s9, v74
	v_and_or_b32 v66, v79, s9, v78
	v_and_or_b32 v67, v77, s9, v76
	global_store_dwordx2 v[58:59], v[60:61], off sc1
	global_store_dwordx2 v[58:59], v[62:63], off offset:512 sc1
	global_store_dwordx2 v[58:59], v[64:65], off offset:1024 sc1
	global_store_dwordx2 v[58:59], v[66:67], off offset:1536 sc1
	s_cbranch_scc1 .LBB0_418
	s_add_i32 s38, s38, s40
	s_add_i32 s8, s8, s40
	s_cmp_lt_i32 s38, 0x8000
	v_lshl_add_u64 v[40:41], v[40:41], 0, s[42:43]
	s_cbranch_scc1 .LBB0_417

; template <int MODE, bool XB> __device__ __forceinline__ void norm_pass(const void* __restrict__ X, const float* __restrict__ g, const float* __restrict__ shift, const float* __restrict__ scale, ...
;     ...
;         for (int r = 0; r < 16; ++r) {
;             f32x4 v[4]; float s = 0.f;
; #pragma unroll
;             for (int j = 0; j < 4; ++j) {
;                 if constexpr (XB) { const v2u w = *(const v2u*)((const bf16*)X + (size_t)(m0 + r) * D + 4 * lane + 256 * j);
;                     v[j] = (f32x4){__uint_as_float(w.x << 16), __uint_as_float(w.x & 0xffff0000u), __uint_as_float(w.y << 16), __uint_as_float(w.y & 0xffff0000u)}; }
;                 else v[j] = *(const f32x4*)((const float*)X + (size_t)(m0 + r) * D + 4 * lane + 256 * j);
;                 s += (v[j][0] * v[j][0] + v[j][1] * v[j][1]) + (v[j][2] * v[j][2] + v[j][3] * v[j][3]); }
.LBB0_962:
	v_lshl_add_u64 v[58:59], v[40:41], 0, s[42:43]
	s_add_i32 s6, s44, -2
	s_add_i32 s10, s44, -1
	v_add_co_u32_e64 v60, s[0:1], s21, v58
	s_ashr_i32 s7, s6, 31
	s_ashr_i32 s45, s44, 31
	v_add_co_u32_e32 v62, vcc, 0x13000000, v58
	v_addc_co_u32_e64 v61, s[0:1], 0, v59, s[0:1]
	s_ashr_i32 s11, s10, 31
	s_lshl_b64 s[6:7], s[6:7], 11
	s_lshl_b64 s[0:1], s[44:45], 11
	v_addc_co_u32_e32 v63, vcc, 0, v59, vcc
	s_lshl_b64 s[10:11], s[10:11], 11
	v_lshl_add_u64 v[82:83], v[32:33], 0, s[6:7]
	v_lshl_add_u64 v[64:65], v[32:33], 0, s[0:1]
	global_load_dwordx2 v[66:67], v[62:63], off
	global_load_dwordx2 v[68:69], v[62:63], off offset:512
	global_load_dwordx2 v[70:71], v[62:63], off offset:1024
	global_load_dwordx2 v[72:73], v[62:63], off offset:1536
	global_load_dwordx2 v[74:75], v[64:65], off
	global_load_dwordx2 v[76:77], v[64:65], off offset:512
	global_load_dwordx2 v[78:79], v[64:65], off offset:1024
	global_load_dwordx2 v[80:81], v[64:65], off offset:1536
	v_lshl_add_u64 v[84:85], v[32:33], 0, s[10:11]
	global_load_dwordx2 v[92:93], v[82:83], off
	global_load_dwordx2 v[98:99], v[82:83], off offset:512
	global_load_dwordx2 v[100:101], v[82:83], off offset:1024
	global_load_dwordx2 v[102:103], v[82:83], off offset:1536
	global_load_dwordx2 v[104:105], v[84:85], off
	global_load_dwordx2 v[106:107], v[84:85], off offset:512
	global_load_dwordx2 v[108:109], v[84:85], off offset:1024
	global_load_dwordx2 v[126:127], v[84:85], off offset:1536
	v_lshl_add_u64 v[58:59], v[34:35], 0, s[0:1]
	v_lshl_add_u64 v[64:65], v[34:35], 0, s[6:7]
	v_lshl_add_u64 v[62:63], v[34:35], 0, s[10:11]
	s_add_i32 s44, s44, 4
	s_add_u32 s42, s42, 0x2000
	s_addc_u32 s43, s43, 0
	s_cmpk_lg_u32 s42, 0x8000
	s_waitcnt vmcnt(15)
	v_and_b32_e32 v83, 0xffff0000, v66
	v_and_b32_e32 v85, 0xffff0000, v67
	v_lshlrev_b32_e32 v82, 16, v66
	v_lshlrev_b32_e32 v84, 16, v67
	s_waitcnt vmcnt(14)
	v_lshlrev_b32_e32 v129, 16, v69
	v_and_b32_e32 v87, 0xffff0000, v69
	v_and_b32_e32 v86, 0xffff0000, v68
	s_waitcnt vmcnt(13)
	v_lshlrev_b32_e32 v88, 16, v70
	v_and_b32_e32 v89, 0xffff0000, v70
	v_lshlrev_b32_e32 v90, 16, v71
	v_and_b32_e32 v91, 0xffff0000, v71
	s_waitcnt vmcnt(12)
	v_lshlrev_b32_e32 v141, 16, v72
	s_waitcnt vmcnt(11)
	v_and_b32_e32 v67, 0xffff0000, v74
	v_and_b32_e32 v69, 0xffff0000, v75
	s_waitcnt vmcnt(10)
	v_and_b32_e32 v71, 0xffff0000, v77
	v_and_b32_e32 v70, 0xffff0000, v76
	v_mul_f32_e32 v122, v85, v85
	v_mul_f32_e32 v140, v83, v83
	s_waitcnt vmcnt(4)
	v_and_b32_e32 v123, 0xffff0000, v102
	v_lshlrev_b32_e32 v128, 16, v68
	v_lshlrev_b32_e32 v94, 16, v73
	v_and_b32_e32 v95, 0xffff0000, v73
	v_lshlrev_b32_e32 v66, 16, v74
	v_lshlrev_b32_e32 v68, 16, v75
	v_lshlrev_b32_e32 v143, 16, v77
	v_lshlrev_b32_e32 v142, 16, v76
	v_and_b32_e32 v73, 0xffff0000, v78
	v_lshlrev_b32_e32 v145, 16, v80
	v_pk_mul_f32 v[146:147], v[86:87], v[86:87]
	v_mov_b32_e32 v149, v141
	v_mul_f32_e32 v144, v89, v89
	v_mul_f32_e32 v148, v91, v91
	v_and_b32_e32 v111, 0xffff0000, v92
	v_lshlrev_b32_e32 v112, 16, v93
	v_and_b32_e32 v113, 0xffff0000, v93
	v_lshlrev_b32_e32 v151, 16, v99
	v_and_b32_e32 v115, 0xffff0000, v99
	v_and_b32_e32 v114, 0xffff0000, v98
	v_lshlrev_b32_e32 v116, 16, v100
	v_and_b32_e32 v117, 0xffff0000, v100
	v_lshlrev_b32_e32 v118, 16, v101
	v_and_b32_e32 v119, 0xffff0000, v101
	v_lshlrev_b32_e32 v153, 16, v102
	s_waitcnt vmcnt(3)
	v_and_b32_e32 v93, 0xffff0000, v104
	v_and_b32_e32 v99, 0xffff0000, v105
	s_waitcnt vmcnt(2)
	v_and_b32_e32 v101, 0xffff0000, v107
	v_and_b32_e32 v100, 0xffff0000, v106
	s_waitcnt vmcnt(0)
	v_lshlrev_b32_e32 v157, 16, v126
	v_mul_f32_e32 v152, v69, v69
	v_pk_mul_f32 v[158:159], v[70:71], v[70:71]
	v_mul_f32_e32 v156, v67, v67
	v_pk_fma_f32 v[164:165], v[84:85], v[84:85], v[122:123] op_sel_hi:[1,1,0]
	v_pk_fma_f32 v[166:167], v[82:83], v[82:83], v[140:141] op_sel_hi:[1,1,0]
	v_and_b32_e32 v97, 0xffff0000, v72
	v_lshlrev_b32_e32 v72, 16, v78
	v_lshlrev_b32_e32 v74, 16, v79
	v_and_b32_e32 v75, 0xffff0000, v79
	v_and_b32_e32 v79, 0xffff0000, v80
	v_lshlrev_b32_e32 v76, 16, v81
	v_and_b32_e32 v77, 0xffff0000, v81
	v_lshlrev_b32_e32 v110, 16, v92
	v_lshlrev_b32_e32 v150, 16, v98
	v_lshlrev_b32_e32 v92, 16, v104
	v_lshlrev_b32_e32 v98, 16, v105
	v_lshlrev_b32_e32 v155, 16, v107
	v_lshlrev_b32_e32 v154, 16, v106
	v_mov_b32_e32 v161, v145
	v_mul_f32_e32 v160, v73, v73
	v_mov_b32_e32 v80, v142
	v_mov_b32_e32 v81, v70
	v_mov_b32_e32 v70, v143
	v_pk_fma_f32 v[146:147], v[128:129], v[128:129], v[146:147]
	v_pk_fma_f32 v[168:169], v[88:89], v[88:89], v[144:145] op_sel_hi:[1,1,0]
	v_pk_fma_f32 v[170:171], v[90:91], v[90:91], v[148:149] op_sel_hi:[1,1,0]
	v_mul_f32_e32 v144, v113, v113
	v_pk_mul_f32 v[172:173], v[114:115], v[114:115]
	v_mul_f32_e32 v174, v111, v111
	v_mul_f32_e32 v180, v99, v99
	v_pk_mul_f32 v[182:183], v[100:101], v[100:101]
	v_mul_f32_e32 v184, v93, v93
	v_mov_b32_e32 v175, v157
	v_pk_fma_f32 v[192:193], v[68:69], v[68:69], v[152:153] op_sel_hi:[1,1,0]
	v_pk_fma_f32 v[142:143], v[142:143], v[142:143], v[158:159]
	v_pk_fma_f32 v[158:159], v[66:67], v[66:67], v[156:157] op_sel_hi:[1,1,0]
	v_mov_b32_e32 v140, v166
	v_mov_b32_e32 v148, v164
	v_mul_f32_e32 v139, v97, v97
	v_mul_f32_e32 v177, v94, v94
	v_mul_f32_e32 v179, v95, v95
	v_mov_b32_e32 v124, v128
	v_mov_b32_e32 v125, v86
	v_mov_b32_e32 v86, v129
	v_mov_b32_e32 v96, v141
	v_lshlrev_b32_e32 v120, 16, v103
	v_and_b32_e32 v121, 0xffff0000, v103
	v_and_b32_e32 v103, 0xffff0000, v108
	v_lshlrev_b32_e32 v104, 16, v109
	v_and_b32_e32 v105, 0xffff0000, v109
	v_and_b32_e32 v109, 0xffff0000, v126
	v_lshlrev_b32_e32 v106, 16, v127
	v_and_b32_e32 v107, 0xffff0000, v127
	v_mul_f32_e32 v162, v75, v75
; template <int MODE, bool XB> __device__ __forceinline__ void norm_pass(const void* __restrict__ X, const float* __restrict__ g, const float* __restrict__ shift, const float* __restrict__ scale, ...
;     ...
;                 if constexpr (XB) { const v2u w = *(const v2u*)((const bf16*)X + (size_t)(m0 + r) * D + 4 * lane + 256 * j);
;                     v[j] = (f32x4){__uint_as_float(w.x << 16), __uint_as_float(w.x & 0xffff0000u), __uint_as_float(w.y << 16), __uint_as_float(w.y & 0xffff0000u)}; }
;                 else v[j] = *(const f32x4*)((const float*)X + (size_t)(m0 + r) * D + 4 * lane + 256 * j);
;                 s += (v[j][0] * v[j][0] + v[j][1] * v[j][1]) + (v[j][2] * v[j][2] + v[j][3] * v[j][3]); }
;             const float rstd = 1.0f / sqrtf(wave_sum(s) * (1.f / D) + 1e-6f);
	v_mov_b32_e32 v163, v153
	v_mov_b32_e32 v128, v150
	v_mov_b32_e32 v129, v114
	v_mov_b32_e32 v114, v151
	v_mov_b32_e32 v126, v154
	v_mov_b32_e32 v127, v100
	v_mov_b32_e32 v100, v155
	v_pk_fma_f32 v[194:195], v[72:73], v[72:73], v[160:161] op_sel_hi:[1,1,0]
	v_pk_add_f32 v[164:165], v[166:167], v[164:165]
	v_pk_add_f32 v[146:147], v[146:147], v[146:147] op_sel:[0,1] op_sel_hi:[1,0]
	v_pk_fma_f32 v[166:167], v[112:113], v[112:113], v[144:145] op_sel_hi:[1,1,0]
	v_pk_fma_f32 v[150:151], v[150:151], v[150:151], v[172:173]
	v_pk_fma_f32 v[172:173], v[110:111], v[110:111], v[174:175] op_sel_hi:[1,1,0]
	v_pk_fma_f32 v[180:181], v[98:99], v[98:99], v[180:181] op_sel_hi:[1,1,0]
	v_pk_fma_f32 v[154:155], v[154:155], v[154:155], v[182:183]
	v_pk_fma_f32 v[182:183], v[92:93], v[92:93], v[184:185] op_sel_hi:[1,1,0]
	v_mov_b32_e32 v144, v158
	v_mov_b32_e32 v160, v192
	v_pk_mul_f32 v[140:141], v[140:141], v[148:149]
	v_lshlrev_b32_e32 v102, 16, v108
	v_mul_f32_e32 v191, v79, v79
	v_mul_f32_e32 v198, v76, v76
	v_mul_f32_e32 v199, v77, v77
	v_mov_b32_e32 v78, v145
	v_mul_f32_e32 v176, v117, v117
	v_mul_f32_e32 v178, v119, v119
	v_mul_f32_e32 v186, v103, v103
	v_mul_f32_e32 v190, v105, v105
	v_pk_fma_f32 v[196:197], v[74:75], v[74:75], v[162:163] op_sel_hi:[1,1,0]
	v_mov_b32_e32 v169, v177
	v_mov_b32_e32 v171, v179
	v_pk_add_f32 v[158:159], v[158:159], v[192:193]
	v_pk_add_f32 v[142:143], v[142:143], v[142:143] op_sel:[0,1] op_sel_hi:[1,0]
	v_mov_b32_e32 v147, v139
	v_mov_b32_e32 v152, v172
	v_mov_b32_e32 v162, v166
	v_mov_b32_e32 v156, v182
	v_mov_b32_e32 v174, v180
	v_pk_mul_f32 v[144:145], v[144:145], v[160:161]
	v_mov_b32_e32 v165, v141
	v_mul_f32_e32 v200, v123, v123
	v_mul_f32_e32 v201, v120, v120
	v_mul_f32_e32 v202, v121, v121
	v_mul_f32_e32 v203, v109, v109
	v_mul_f32_e32 v204, v106, v106
	v_mul_f32_e32 v205, v107, v107
	v_mov_b32_e32 v108, v157
	v_pk_fma_f32 v[176:177], v[116:117], v[116:117], v[176:177] op_sel_hi:[1,1,0]
	v_pk_fma_f32 v[178:179], v[118:119], v[118:119], v[178:179] op_sel_hi:[1,1,0]
	v_pk_fma_f32 v[184:185], v[102:103], v[102:103], v[186:187] op_sel_hi:[1,1,0]
	v_pk_fma_f32 v[186:187], v[104:105], v[104:105], v[190:191] op_sel_hi:[1,1,0]
	v_mov_b32_e32 v195, v198
	v_mov_b32_e32 v197, v199
	v_pk_add_f32 v[148:149], v[168:169], v[170:171]
	v_pk_add_f32 v[166:167], v[172:173], v[166:167]
	v_pk_add_f32 v[150:151], v[150:151], v[150:151] op_sel:[0,1] op_sel_hi:[1,0]
	v_pk_add_f32 v[168:169], v[182:183], v[180:181]
	v_pk_add_f32 v[154:155], v[154:155], v[154:155] op_sel:[0,1] op_sel_hi:[1,0]
	v_mov_b32_e32 v143, v191
	v_pk_mul_f32 v[140:141], v[152:153], v[162:163]
	v_pk_mul_f32 v[156:157], v[156:157], v[174:175]
	v_mov_b32_e32 v159, v145
	v_pk_add_f32 v[144:145], v[164:165], v[146:147]
	v_mov_b32_e32 v177, v201
	v_mov_b32_e32 v179, v202
	v_mov_b32_e32 v185, v204
	v_mov_b32_e32 v187, v205
	v_pk_add_f32 v[160:161], v[194:195], v[196:197]
	v_mov_b32_e32 v151, v200
	v_mov_b32_e32 v155, v203
	v_mov_b32_e32 v167, v141
	v_mov_b32_e32 v169, v157
	v_pk_add_f32 v[140:141], v[158:159], v[142:143]
	v_pk_add_f32 v[142:143], v[144:145], v[148:149]
	v_mov_b32_e32 v122, v153
	v_pk_add_f32 v[152:153], v[176:177], v[178:179]
	v_pk_add_f32 v[162:163], v[184:185], v[186:187]
	v_pk_add_f32 v[144:145], v[166:167], v[150:151]
	v_pk_add_f32 v[146:147], v[168:169], v[154:155]
	v_pk_add_f32 v[140:141], v[140:141], v[160:161]
	v_add_f32_e32 v139, v142, v143
	v_pk_add_f32 v[142:143], v[144:145], v[152:153]
	v_pk_add_f32 v[144:145], v[146:147], v[162:163]
	v_add_f32_e32 v140, v140, v141
	ds_bpermute_b32 v141, v130, v139
	v_add_f32_e32 v142, v142, v143
	ds_bpermute_b32 v143, v130, v140
	v_add_f32_e32 v144, v144, v145
	ds_bpermute_b32 v145, v130, v142
	ds_bpermute_b32 v146, v130, v144
	s_waitcnt lgkmcnt(3)
	v_add_f32_e32 v139, v139, v141
	s_waitcnt lgkmcnt(2)
	v_add_f32_e32 v140, v140, v143
	ds_bpermute_b32 v141, v131, v139
	s_waitcnt lgkmcnt(2)
	v_add_f32_e32 v142, v142, v145
	ds_bpermute_b32 v143, v131, v140
	s_waitcnt lgkmcnt(2)
	v_add_f32_e32 v144, v144, v146
	ds_bpermute_b32 v145, v131, v142
	ds_bpermute_b32 v146, v131, v144
	s_waitcnt lgkmcnt(3)
	v_add_f32_e32 v139, v139, v141
	s_waitcnt lgkmcnt(2)
	v_add_f32_e32 v140, v140, v143
	ds_bpermute_b32 v141, v132, v139
	s_waitcnt lgkmcnt(2)
	v_add_f32_e32 v142, v142, v145
	ds_bpermute_b32 v143, v132, v140
	s_waitcnt lgkmcnt(2)
	v_add_f32_e32 v144, v144, v146
	ds_bpermute_b32 v145, v132, v142
	ds_bpermute_b32 v146, v132, v144
	s_waitcnt lgkmcnt(3)
	v_add_f32_e32 v139, v139, v141
	s_waitcnt lgkmcnt(2)
	v_add_f32_e32 v140, v140, v143
	ds_bpermute_b32 v141, v133, v139
	s_waitcnt lgkmcnt(2)
	v_add_f32_e32 v142, v142, v145
	ds_bpermute_b32 v143, v133, v140
	s_waitcnt lgkmcnt(2)
	v_add_f32_e32 v144, v144, v146
	ds_bpermute_b32 v145, v133, v142
	ds_bpermute_b32 v146, v133, v144
	s_waitcnt lgkmcnt(3)
	v_add_f32_e32 v139, v139, v141
	s_waitcnt lgkmcnt(2)
	v_add_f32_e32 v140, v140, v143
	ds_bpermute_b32 v141, v134, v139
	s_waitcnt lgkmcnt(2)
	v_add_f32_e32 v142, v142, v145
	ds_bpermute_b32 v143, v134, v140
	s_waitcnt lgkmcnt(2)
	v_add_f32_e32 v144, v144, v146
	ds_bpermute_b32 v145, v134, v142
	ds_bpermute_b32 v146, v134, v144
	s_waitcnt lgkmcnt(3)
	v_add_f32_e32 v139, v139, v141
	s_waitcnt lgkmcnt(2)
	v_add_f32_e32 v140, v140, v143
	ds_bpermute_b32 v141, v135, v139
	s_waitcnt lgkmcnt(2)
	v_add_f32_e32 v142, v142, v145
	ds_bpermute_b32 v143, v135, v140
	s_waitcnt lgkmcnt(2)
	v_add_f32_e32 v144, v144, v146
	ds_bpermute_b32 v145, v135, v142
	ds_bpermute_b32 v146, v135, v144
	s_waitcnt lgkmcnt(3)
	v_add_f32_e32 v139, v139, v141
	s_waitcnt lgkmcnt(2)
	v_add_f32_e32 v140, v140, v143
	v_fmamk_f32 v139, v139, 0x3a800000, v137
	s_waitcnt lgkmcnt(1)
; __device__ __forceinline__ unsigned pk2(float lo, float hi) { return f2bf(lo) | (f2bf(hi) << 16); }
; template <int MODE, bool XB> __device__ __forceinline__ void norm_pass(const void* __restrict__ X, const float* __restrict__ g, const float* __restrict__ shift, const float* __restrict__ scale, ...
;     ...
;             const float rstd = 1.0f / sqrtf(wave_sum(s) * (1.f / D) + 1e-6f);
; #pragma unroll
;             for (int j = 0; j < 4; ++j) {
;                 if (MODE == 0) { const f32x4 o = v[j] * rstd * gm[j] + sh[j]; v2u w; w.x = pk2(o[0], o[1]); w.y = pk2(o[2], o[3]); *(v2u*)(Hb + (size_t)(m0 + r) * D + 4 * lane + 256 * j) = w; }
	v_add_f32_e32 v141, v142, v145
	s_waitcnt lgkmcnt(0)
	v_add_f32_e32 v142, v144, v146
	v_fmamk_f32 v140, v140, 0x3a800000, v137
	v_mul_f32_e32 v143, 0x4f800000, v139
	v_cmp_gt_f32_e64 s[0:1], s12, v139
	v_fmamk_f32 v141, v141, 0x3a800000, v137
	v_fmamk_f32 v142, v142, 0x3a800000, v137
	v_mul_f32_e32 v144, 0x4f800000, v140
	v_cmp_gt_f32_e32 vcc, s12, v140
	v_cndmask_b32_e64 v139, v139, v143, s[0:1]
	v_mul_f32_e32 v143, 0x4f800000, v141
	v_cmp_gt_f32_e64 s[6:7], s12, v141
	v_mul_f32_e32 v145, 0x4f800000, v142
	v_cmp_gt_f32_e64 s[10:11], s12, v142
	v_cndmask_b32_e32 v140, v140, v144, vcc
	v_sqrt_f32_e32 v144, v139
	v_cndmask_b32_e64 v141, v141, v143, s[6:7]
	v_cndmask_b32_e64 v142, v142, v145, s[10:11]
	v_sqrt_f32_e32 v143, v140
	v_sqrt_f32_e32 v145, v141
	v_sqrt_f32_e32 v146, v142
	v_add_u32_e32 v147, -1, v144
	v_add_u32_e32 v148, 1, v144
	v_add_u32_e32 v149, -1, v143
	v_fma_f32 v151, -v147, v144, v139
	v_add_u32_e32 v150, 1, v143
	v_fma_f32 v152, -v148, v144, v139
	v_add_u32_e32 v153, -1, v145
	v_add_u32_e32 v155, -1, v146
	v_fma_f32 v157, -v149, v143, v140
	v_cmp_ge_f32_e64 s[14:15], 0, v151
	v_add_u32_e32 v154, 1, v145
	v_add_u32_e32 v156, 1, v146
	v_fma_f32 v158, -v150, v143, v140
	v_cndmask_b32_e64 v144, v144, v147, s[14:15]
	v_fma_f32 v147, -v153, v145, v141
	v_fma_f32 v159, -v155, v146, v142
	v_cmp_ge_f32_e64 s[14:15], 0, v157
	v_cmp_lt_f32_e64 s[16:17], 0, v152
	v_fma_f32 v151, -v154, v145, v141
	v_fma_f32 v160, -v156, v146, v142
	v_cndmask_b32_e64 v143, v143, v149, s[14:15]
	v_cmp_lt_f32_e64 s[14:15], 0, v158
	v_cndmask_b32_e64 v144, v144, v148, s[16:17]
	v_cmp_ge_f32_e64 s[16:17], 0, v147
	v_cmp_ge_f32_e64 s[18:19], 0, v159
	v_cndmask_b32_e64 v143, v143, v150, s[14:15]
	v_cndmask_b32_e64 v145, v145, v153, s[16:17]
	v_cmp_lt_f32_e64 s[16:17], 0, v151
	v_cndmask_b32_e64 v146, v146, v155, s[18:19]
	v_cmp_lt_f32_e64 s[18:19], 0, v160
	v_mul_f32_e32 v147, 0x37800000, v144
	v_cndmask_b32_e64 v145, v145, v154, s[16:17]
	v_cndmask_b32_e64 v146, v146, v156, s[18:19]
	v_mul_f32_e32 v148, 0x37800000, v143
	v_cndmask_b32_e64 v144, v144, v147, s[0:1]
	v_cmp_class_f32_e64 s[0:1], v139, v138
	v_mul_f32_e32 v147, 0x37800000, v145
	v_mul_f32_e32 v149, 0x37800000, v146
	v_cndmask_b32_e32 v143, v143, v148, vcc
	v_cmp_class_f32_e32 vcc, v140, v138
	v_cndmask_b32_e64 v139, v144, v139, s[0:1]
	v_cndmask_b32_e64 v144, v145, v147, s[6:7]
	v_cmp_class_f32_e64 s[0:1], v141, v138
	v_cndmask_b32_e64 v145, v146, v149, s[10:11]
	v_cmp_class_f32_e64 s[6:7], v142, v138
	v_cndmask_b32_e32 v143, v143, v140, vcc
	v_div_scale_f32 v140, s[10:11], v139, v139, 1.0
	v_cndmask_b32_e64 v141, v144, v141, s[0:1]
	v_cndmask_b32_e64 v142, v145, v142, s[6:7]
	v_div_scale_f32 v144, s[0:1], v143, v143, 1.0
	v_rcp_f32_e32 v147, v140
	v_div_scale_f32 v148, s[6:7], v141, v141, 1.0
	v_div_scale_f32 v150, s[10:11], v142, v142, 1.0
	v_rcp_f32_e32 v152, v144
	v_rcp_f32_e32 v153, v148
	v_rcp_f32_e32 v154, v150
	v_fma_f32 v155, -v140, v147, 1.0
	v_div_scale_f32 v146, vcc, 1.0, v139, 1.0
	v_fma_f32 v156, -v144, v152, 1.0
	v_fmac_f32_e32 v147, v155, v147
	v_fma_f32 v155, -v148, v153, 1.0
	v_fma_f32 v157, -v150, v154, 1.0
	v_fmac_f32_e32 v152, v156, v152
	v_mul_f32_e32 v156, v146, v147
	v_div_scale_f32 v145, s[0:1], 1.0, v143, 1.0
	v_div_scale_f32 v149, s[6:7], 1.0, v141, 1.0
	v_fmac_f32_e32 v153, v155, v153
	v_fmac_f32_e32 v154, v157, v154
	v_fma_f32 v157, -v140, v156, v146
	v_div_scale_f32 v151, s[10:11], 1.0, v142, 1.0
	v_mul_f32_e32 v155, v145, v152
	v_mul_f32_e32 v158, v149, v153
	v_fmac_f32_e32 v156, v157, v147
	v_mul_f32_e32 v159, v151, v154
	v_fma_f32 v160, -v144, v155, v145
	v_fma_f32 v157, -v148, v158, v149
	v_fma_f32 v140, -v140, v156, v146
	v_fma_f32 v161, -v150, v159, v151
	v_fmac_f32_e32 v155, v160, v152
	v_fmac_f32_e32 v158, v157, v153
	v_div_fmas_f32 v140, v140, v147, v156
	v_fmac_f32_e32 v159, v161, v154
	v_fma_f32 v144, -v144, v155, v145
	v_fma_f32 v145, -v148, v158, v149
	v_div_fixup_f32 v140, v140, v139, 1.0
	s_mov_b64 vcc, s[6:7]
	v_fma_f32 v146, -v150, v159, v151
	v_div_fmas_f32 v139, v145, v153, v158
	v_pk_mul_f32 v[82:83], v[140:141], v[82:83] op_sel_hi:[0,1]
	s_mov_b64 vcc, s[10:11]
	v_pk_mul_f32 v[84:85], v[140:141], v[84:85] op_sel_hi:[0,1]
	v_pk_mul_f32 v[124:125], v[140:141], v[124:125] op_sel_hi:[0,1]
	v_pk_mul_f32 v[86:87], v[140:141], v[86:87] op_sel_hi:[0,1]
	v_pk_mul_f32 v[88:89], v[140:141], v[88:89] op_sel_hi:[0,1]
	v_pk_mul_f32 v[90:91], v[140:141], v[90:91] op_sel_hi:[0,1]
	v_pk_mul_f32 v[96:97], v[96:97], v[140:141] op_sel_hi:[1,0]
	v_pk_mul_f32 v[94:95], v[94:95], v[140:141] op_sel_hi:[1,0]
	v_div_fixup_f32 v140, v139, v141, 1.0
	v_div_fmas_f32 v139, v146, v154, v159
	v_pk_fma_f32 v[82:83], v[44:45], v[82:83], v[16:17]
	s_mov_b64 vcc, s[0:1]
	v_pk_fma_f32 v[84:85], v[42:43], v[84:85], v[18:19]
	v_pk_fma_f32 v[86:87], v[46:47], v[86:87], v[22:23]
	v_pk_fma_f32 v[124:125], v[48:49], v[124:125], v[20:21]
	v_pk_fma_f32 v[90:91], v[50:51], v[90:91], v[26:27]
	v_pk_fma_f32 v[88:89], v[52:53], v[88:89], v[24:25]
	v_pk_fma_f32 v[94:95], v[54:55], v[94:95], v[30:31]
	v_pk_fma_f32 v[96:97], v[56:57], v[96:97], v[28:29]
	v_pk_mul_f32 v[110:111], v[140:141], v[110:111] op_sel_hi:[0,1]
	v_pk_mul_f32 v[112:113], v[140:141], v[112:113] op_sel_hi:[0,1]
	v_pk_mul_f32 v[128:129], v[140:141], v[128:129] op_sel_hi:[0,1]
	v_pk_mul_f32 v[114:115], v[140:141], v[114:115] op_sel_hi:[0,1]
	v_pk_mul_f32 v[116:117], v[140:141], v[116:117] op_sel_hi:[0,1]
	v_pk_mul_f32 v[118:119], v[140:141], v[118:119] op_sel_hi:[0,1]
	v_pk_mul_f32 v[122:123], v[122:123], v[140:141] op_sel_hi:[1,0]
	v_pk_mul_f32 v[120:121], v[120:121], v[140:141] op_sel_hi:[1,0]
	v_div_fixup_f32 v140, v139, v142, 1.0
; __device__ __forceinline__ unsigned pk2(float lo, float hi) { return f2bf(lo) | (f2bf(hi) << 16); }
; template <int MODE, bool XB> __device__ __forceinline__ void norm_pass(const void* __restrict__ X, const float* __restrict__ g, const float* __restrict__ shift, const float* __restrict__ scale, ...
;     ...
;             for (int j = 0; j < 4; ++j) {
;                 if (MODE == 0) { const f32x4 o = v[j] * rstd * gm[j] + sh[j]; v2u w; w.x = pk2(o[0], o[1]); w.y = pk2(o[2], o[3]); *(v2u*)(Hb + (size_t)(m0 + r) * D + 4 * lane + 256 * j) = w; }
	v_div_fmas_f32 v139, v144, v152, v155
	v_bfe_u32 v141, v82, 16, 1
	v_bfe_u32 v142, v83, 16, 1
	v_bfe_u32 v144, v84, 16, 1
	v_bfe_u32 v145, v85, 16, 1
	v_bfe_u32 v146, v124, 16, 1
	v_bfe_u32 v147, v125, 16, 1
	v_bfe_u32 v148, v86, 16, 1
	v_bfe_u32 v149, v87, 16, 1
	v_bfe_u32 v150, v88, 16, 1
	v_bfe_u32 v151, v89, 16, 1
	v_bfe_u32 v152, v90, 16, 1
	v_bfe_u32 v154, v96, 16, 1
	v_bfe_u32 v156, v94, 16, 1
	v_pk_fma_f32 v[112:113], v[42:43], v[112:113], v[18:19]
	v_pk_fma_f32 v[110:111], v[44:45], v[110:111], v[16:17]
	v_pk_fma_f32 v[114:115], v[46:47], v[114:115], v[22:23]
	v_pk_fma_f32 v[128:129], v[48:49], v[128:129], v[20:21]
	v_pk_fma_f32 v[118:119], v[50:51], v[118:119], v[26:27]
	v_pk_fma_f32 v[116:117], v[52:53], v[116:117], v[24:25]
	v_pk_fma_f32 v[122:123], v[56:57], v[122:123], v[28:29]
	v_pk_mul_f32 v[92:93], v[140:141], v[92:93] op_sel_hi:[0,1]
	v_pk_mul_f32 v[98:99], v[140:141], v[98:99] op_sel_hi:[0,1]
	v_pk_mul_f32 v[126:127], v[140:141], v[126:127] op_sel_hi:[0,1]
	v_pk_mul_f32 v[100:101], v[140:141], v[100:101] op_sel_hi:[0,1]
	v_pk_mul_f32 v[102:103], v[140:141], v[102:103] op_sel_hi:[0,1]
	v_pk_mul_f32 v[104:105], v[140:141], v[104:105] op_sel_hi:[0,1]
	v_pk_mul_f32 v[108:109], v[108:109], v[140:141] op_sel_hi:[1,0]
	v_pk_mul_f32 v[106:107], v[106:107], v[140:141] op_sel_hi:[1,0]
	v_div_fixup_f32 v140, v139, v143, 1.0
	v_add3_u32 v139, v82, v141, s13
	v_add3_u32 v141, v83, v142, s13
	v_bfe_u32 v153, v91, 16, 1
	v_bfe_u32 v155, v97, 16, 1
	v_bfe_u32 v157, v95, 16, 1
	v_pk_fma_f32 v[120:121], v[54:55], v[120:121], v[30:31]
	v_add3_u32 v142, v84, v144, s13
	v_add3_u32 v143, v85, v145, s13
	v_add3_u32 v124, v124, v146, s13
	v_add3_u32 v125, v125, v147, s13
	v_add3_u32 v144, v86, v148, s13
	v_add3_u32 v145, v87, v149, s13
	v_add3_u32 v146, v88, v150, s13
	v_add3_u32 v147, v89, v151, s13
	v_add3_u32 v148, v90, v152, s13
	v_add3_u32 v150, v96, v154, s13
	v_add3_u32 v152, v94, v156, s13
	v_bfe_u32 v154, v110, 16, 1
	v_bfe_u32 v156, v112, 16, 1
	v_bfe_u32 v158, v128, 16, 1
	v_bfe_u32 v160, v114, 16, 1
	v_bfe_u32 v162, v116, 16, 1
	v_bfe_u32 v164, v118, 16, 1
	v_bfe_u32 v166, v122, 16, 1
	v_pk_fma_f32 v[82:83], v[42:43], v[98:99], v[18:19]
	v_pk_fma_f32 v[84:85], v[44:45], v[92:93], v[16:17]
	v_pk_fma_f32 v[86:87], v[46:47], v[100:101], v[22:23]
	v_pk_fma_f32 v[88:89], v[48:49], v[126:127], v[20:21]
	v_pk_mul_f32 v[66:67], v[140:141], v[66:67] op_sel_hi:[0,1]
	v_pk_mul_f32 v[68:69], v[140:141], v[68:69] op_sel_hi:[0,1]
	v_add3_u32 v149, v91, v153, s13
	v_add3_u32 v151, v97, v155, s13
	v_add3_u32 v153, v95, v157, s13
	v_bfe_u32 v155, v111, 16, 1
	v_bfe_u32 v157, v113, 16, 1
	v_bfe_u32 v159, v129, 16, 1
	v_bfe_u32 v161, v115, 16, 1
	v_bfe_u32 v163, v117, 16, 1
	v_bfe_u32 v165, v119, 16, 1
	v_bfe_u32 v167, v123, 16, 1
	v_bfe_u32 v168, v120, 16, 1
	v_pk_fma_f32 v[90:91], v[50:51], v[104:105], v[26:27]
	v_pk_fma_f32 v[92:93], v[52:53], v[102:103], v[24:25]
	v_pk_fma_f32 v[94:95], v[54:55], v[106:107], v[30:31]
	v_pk_fma_f32 v[96:97], v[56:57], v[108:109], v[28:29]
	v_pk_mul_f32 v[80:81], v[140:141], v[80:81] op_sel_hi:[0,1]
	v_pk_mul_f32 v[70:71], v[140:141], v[70:71] op_sel_hi:[0,1]
	v_pk_mul_f32 v[72:73], v[140:141], v[72:73] op_sel_hi:[0,1]
	v_pk_mul_f32 v[74:75], v[140:141], v[74:75] op_sel_hi:[0,1]
	v_pk_mul_f32 v[78:79], v[78:79], v[140:141] op_sel_hi:[1,0]
	v_pk_mul_f32 v[76:77], v[76:77], v[140:141] op_sel_hi:[1,0]
	v_lshrrev_b32_e32 v98, 16, v139
	v_lshrrev_b32_e32 v99, 16, v142
	v_lshrrev_b32_e32 v100, 16, v124
	v_lshrrev_b32_e32 v101, 16, v144
	v_lshrrev_b32_e32 v103, 16, v148
	v_add3_u32 v106, v110, v154, s13
	v_add3_u32 v108, v112, v156, s13
	v_add3_u32 v110, v128, v158, s13
	v_add3_u32 v112, v114, v160, s13
	v_add3_u32 v114, v116, v162, s13
	v_add3_u32 v116, v118, v164, s13
	v_add3_u32 v118, v122, v166, s13
	v_bfe_u32 v122, v84, 16, 1
	v_bfe_u32 v124, v82, 16, 1
	v_bfe_u32 v127, v88, 16, 1
	v_bfe_u32 v128, v89, 16, 1
	v_bfe_u32 v139, v87, 16, 1
	v_pk_fma_f32 v[68:69], v[42:43], v[68:69], v[18:19]
	v_pk_fma_f32 v[66:67], v[44:45], v[66:67], v[16:17]
	v_bfe_u32 v169, v121, 16, 1
	v_lshrrev_b32_e32 v102, 16, v146
	v_lshrrev_b32_e32 v104, 16, v150
	v_lshrrev_b32_e32 v105, 16, v152
	v_add3_u32 v107, v111, v155, s13
	v_add3_u32 v109, v113, v157, s13
	v_add3_u32 v111, v129, v159, s13
	v_add3_u32 v113, v115, v161, s13
	v_add3_u32 v115, v117, v163, s13
	v_add3_u32 v117, v119, v165, s13
	v_add3_u32 v119, v123, v167, s13
	v_add3_u32 v120, v120, v168, s13
	v_bfe_u32 v123, v85, 16, 1
	v_bfe_u32 v126, v83, 16, 1
	v_bfe_u32 v129, v86, 16, 1
	v_bfe_u32 v140, v92, 16, 1
	v_bfe_u32 v144, v90, 16, 1
	v_bfe_u32 v148, v96, 16, 1
	v_bfe_u32 v152, v94, 16, 1
	v_pk_fma_f32 v[70:71], v[46:47], v[70:71], v[22:23]
	v_pk_fma_f32 v[80:81], v[48:49], v[80:81], v[20:21]
	v_pk_fma_f32 v[74:75], v[50:51], v[74:75], v[26:27]
; __device__ __forceinline__ unsigned pk2(float lo, float hi) { return f2bf(lo) | (f2bf(hi) << 16); }
; template <int MODE, bool XB> __device__ __forceinline__ void norm_pass(const void* __restrict__ X, const float* __restrict__ g, const float* __restrict__ shift, const float* __restrict__ scale, ...
;     ...
;     for (int m0 = gw * 16; m0 < M; m0 += NGW * 16) {
;         const int b = m0 / SEQ;
;         f32x4 gm[4], sh[4];
; #pragma unroll
;         for (int j = 0; j < 4; ++j) { const int col = 4 * lane + 256 * j; gm[j] = *(const f32x4*)(g + col);
;             if (MODE == 0) { gm[j] = gm[j] * (*(const f32x4*)(scale + (size_t)b * NMOD9 + col) + 1.0f); sh[j] = *(const f32x4*)(shift + (size_t)b * NMOD9 + col); } }
; #pragma unroll 4
;         for (int r = 0; r < 16; ++r) {
;     ...
;             for (int j = 0; j < 4; ++j) {
;                 if (MODE == 0) { const f32x4 o = v[j] * rstd * gm[j] + sh[j]; v2u w; w.x = pk2(o[0], o[1]); w.y = pk2(o[2], o[3]); *(v2u*)(Hb + (size_t)(m0 + r) * D + 4 * lane + 256 * j) = w; }
	v_pk_fma_f32 v[72:73], v[52:53], v[72:73], v[24:25]
	v_pk_fma_f32 v[76:77], v[54:55], v[76:77], v[30:31]
	v_pk_fma_f32 v[78:79], v[56:57], v[78:79], v[28:29]
	v_and_or_b32 v98, v141, s9, v98
	v_and_or_b32 v99, v143, s9, v99
	v_and_or_b32 v101, v145, s9, v101
	v_and_or_b32 v103, v149, s9, v103
	v_lshrrev_b32_e32 v106, 16, v106
	v_lshrrev_b32_e32 v108, 16, v108
	v_lshrrev_b32_e32 v110, 16, v110
	v_lshrrev_b32_e32 v112, 16, v112
	v_add3_u32 v122, v84, v122, s13
	v_add3_u32 v124, v82, v124, s13
	v_add3_u32 v88, v88, v127, s13
	v_add3_u32 v89, v89, v128, s13
	v_add3_u32 v127, v87, v139, s13
	v_bfe_u32 v128, v66, 16, 1
	v_bfe_u32 v139, v68, 16, 1
	v_add3_u32 v121, v121, v169, s13
	v_bfe_u32 v142, v93, 16, 1
	v_bfe_u32 v146, v91, 16, 1
	v_bfe_u32 v150, v97, 16, 1
	v_bfe_u32 v154, v95, 16, 1
	v_and_or_b32 v100, v125, s9, v100
	v_and_or_b32 v102, v147, s9, v102
	v_and_or_b32 v104, v151, s9, v104
	v_and_or_b32 v105, v153, s9, v105
	v_lshrrev_b32_e32 v114, 16, v114
	v_lshrrev_b32_e32 v116, 16, v116
	v_lshrrev_b32_e32 v118, 16, v118
	v_lshrrev_b32_e32 v120, 16, v120
	v_add3_u32 v123, v85, v123, s13
	v_add3_u32 v125, v83, v126, s13
	v_add3_u32 v126, v86, v129, s13
	v_add3_u32 v92, v92, v140, s13
	v_add3_u32 v90, v90, v144, s13
	v_add3_u32 v96, v96, v148, s13
	v_add3_u32 v94, v94, v152, s13
	v_bfe_u32 v129, v67, 16, 1
	v_bfe_u32 v140, v69, 16, 1
	v_bfe_u32 v141, v80, 16, 1
	v_bfe_u32 v143, v70, 16, 1
	v_bfe_u32 v145, v72, 16, 1
	v_bfe_u32 v147, v74, 16, 1
	v_bfe_u32 v149, v78, 16, 1
	v_bfe_u32 v151, v76, 16, 1
	global_store_dwordx2 v[60:61], v[98:99], off sc1
	global_store_dwordx2 v[60:61], v[100:101], off offset:512 sc1
	global_store_dwordx2 v[60:61], v[102:103], off offset:1024 sc1
	global_store_dwordx2 v[60:61], v[104:105], off offset:1536 sc1
	v_and_or_b32 v60, v107, s9, v106
	v_and_or_b32 v61, v109, s9, v108
	v_and_or_b32 v82, v111, s9, v110
	v_and_or_b32 v83, v113, s9, v112
	v_lshrrev_b32_e32 v98, 16, v122
	v_lshrrev_b32_e32 v99, 16, v124
	v_add3_u32 v101, v66, v128, s13
	v_add3_u32 v103, v68, v139, s13
	v_add3_u32 v93, v93, v142, s13
	v_add3_u32 v91, v91, v146, s13
	v_add3_u32 v97, v97, v150, s13
	v_add3_u32 v95, v95, v154, s13
	v_bfe_u32 v142, v81, 16, 1
	v_bfe_u32 v144, v71, 16, 1
	v_bfe_u32 v146, v73, 16, 1
	v_bfe_u32 v148, v75, 16, 1
	v_bfe_u32 v150, v79, 16, 1
	v_bfe_u32 v152, v77, 16, 1
	v_and_or_b32 v84, v115, s9, v114
	v_and_or_b32 v85, v117, s9, v116
	v_and_or_b32 v86, v119, s9, v118
	v_and_or_b32 v87, v121, s9, v120
	v_lshrrev_b32_e32 v88, 16, v88
	v_lshrrev_b32_e32 v100, 16, v126
	v_lshrrev_b32_e32 v92, 16, v92
	v_lshrrev_b32_e32 v90, 16, v90
	v_lshrrev_b32_e32 v96, 16, v96
	v_lshrrev_b32_e32 v94, 16, v94
	v_add3_u32 v102, v67, v129, s13
	v_add3_u32 v104, v69, v140, s13
	v_add3_u32 v80, v80, v141, s13
	v_add3_u32 v70, v70, v143, s13
	v_add3_u32 v72, v72, v145, s13
	v_add3_u32 v74, v74, v147, s13
	v_add3_u32 v78, v78, v149, s13
	v_add3_u32 v76, v76, v151, s13
	global_store_dwordx2 v[64:65], v[60:61], off sc1
	global_store_dwordx2 v[64:65], v[82:83], off offset:512 sc1
	global_store_dwordx2 v[64:65], v[84:85], off offset:1024 sc1
	global_store_dwordx2 v[64:65], v[86:87], off offset:1536 sc1
	v_and_or_b32 v60, v123, s9, v98
	v_and_or_b32 v61, v125, s9, v99
	v_lshrrev_b32_e32 v82, 16, v101
	v_lshrrev_b32_e32 v83, 16, v103
	v_add3_u32 v81, v81, v142, s13
	v_add3_u32 v71, v71, v144, s13
	v_add3_u32 v73, v73, v146, s13
	v_add3_u32 v75, v75, v148, s13
	v_add3_u32 v79, v79, v150, s13
	v_add3_u32 v77, v77, v152, s13
	v_and_or_b32 v64, v89, s9, v88
	v_and_or_b32 v65, v127, s9, v100
	v_and_or_b32 v66, v93, s9, v92
	v_and_or_b32 v67, v91, s9, v90
	v_and_or_b32 v68, v97, s9, v96
	v_and_or_b32 v69, v95, s9, v94
	v_lshrrev_b32_e32 v80, 16, v80
	v_lshrrev_b32_e32 v70, 16, v70
	v_lshrrev_b32_e32 v72, 16, v72
	v_lshrrev_b32_e32 v74, 16, v74
	v_lshrrev_b32_e32 v78, 16, v78
	v_lshrrev_b32_e32 v76, 16, v76
	global_store_dwordx2 v[62:63], v[60:61], off sc1
	global_store_dwordx2 v[62:63], v[64:65], off offset:512 sc1
	global_store_dwordx2 v[62:63], v[66:67], off offset:1024 sc1
	global_store_dwordx2 v[62:63], v[68:69], off offset:1536 sc1
	v_and_or_b32 v60, v102, s9, v82
	v_and_or_b32 v61, v104, s9, v83
	v_and_or_b32 v62, v81, s9, v80
	v_and_or_b32 v63, v71, s9, v70
	v_and_or_b32 v64, v73, s9, v72
	v_and_or_b32 v65, v75, s9, v74
	v_and_or_b32 v66, v79, s9, v78
	v_and_or_b32 v67, v77, s9, v76
	global_store_dwordx2 v[58:59], v[60:61], off sc1
	global_store_dwordx2 v[58:59], v[62:63], off offset:512 sc1
	global_store_dwordx2 v[58:59], v[64:65], off offset:1024 sc1
	global_store_dwordx2 v[58:59], v[66:67], off offset:1536 sc1
	s_cbranch_scc1 .LBB0_962
	s_add_i32 s20, s20, s38
	s_add_i32 s8, s8, s38
	s_cmp_lt_i32 s20, 0x8000
	v_lshl_add_u64 v[40:41], v[40:41], 0, s[40:41]
	s_cbranch_scc1 .LBB0_961
